# hand-written lean GDN + mLSTM recurrence loops (SGPR-base addressing, op_sel broadcasts, fewer pads)
# speedup vs baseline: 1.0497x; 1.0497x over previous
.LBB0_123:
	s_andn2_b64 vcc, exec, s[0:1]
	s_cbranch_vccnz .LBB0_252
	s_lshl_b32 s0, s58, 2
	s_bfe_u32 s1, s26, 0x20006
	s_or_b32 s27, s1, s0
	s_lshl_b32 s28, s59, 2
	s_cmpk_lt_i32 s27, 0x400
	s_cselect_b64 s[2:3], -1, 0
	v_readlane_b32 s0, v255, 15
	v_cndmask_b32_e64 v0, 0, 1, s[2:3]
	s_cmp_lt_i32 s0, 4
	s_mov_b64 s[0:1], -1
	v_cmp_ne_u32_e64 s[6:7], 1, v0
	s_cbranch_scc1 .LBB0_186
	s_and_b64 vcc, exec, s[6:7]
	s_cbranch_vccnz .LBB0_185
	v_readlane_b32 s0, v255, 18
	v_readlane_b32 s1, v255, 19
	s_load_dwordx4 s[8:11], s[0:1], 0xe8
	v_and_b32_e32 v0, 15, v198
	v_lshrrev_b32_e32 v5, 4, v198
	v_lshlrev_b32_e32 v2, 3, v0
	v_lshlrev_b32_e32 v105, 4, v0
	v_lshlrev_b32_e32 v104, 11, v0
	s_mov_b32 s19, 0xffff0000
	s_mov_b32 s29, 0x3fb8aa3b
	v_mov_b32_e32 v46, 0xc0400000
	s_mov_b32 s30, s27
	s_waitcnt lgkmcnt(0)
.Lml_item:
	s_lshr_b32 s0, s30, 4
	s_and_b32 s24, s30, 15
	s_mov_b32 s25, s24
	s_lshr_b32 s2, s0, 3
	s_and_b32 s3, s0, 7
	s_lshl_b32 s4, s24, 4
	v_lshl_add_u32 v4, v5, 2, s4
	s_lshl_b32 s5, s3, 7
	v_add_u32_e32 v3, s5, v4
	v_lshl_add_u32 v32, v4, 1, v104
	v_mov_b32_e32 v47, v32
	s_lshl_b32 s4, s2, 25
	s_add_u32 s4, s4, s5
	s_add_u32 s4, s4, 0x3bc2000
	s_add_u32 s12, s10, s4
	s_addc_u32 s13, s11, 0
	s_lshl_b32 s4, s2, 18
	s_lshl_b32 s5, s3, 4
	s_add_u32 s4, s4, s5
	s_add_u32 s4, s4, 0x39bc400
	s_add_u32 s14, s10, s4
	s_addc_u32 s15, s11, 0
	s_mov_b64 s[22:23], s[14:15]
	s_lshl_b32 s4, s2, 23
	s_lshl_b32 s5, s3, 8
	s_add_u32 s4, s4, s5
	s_add_u32 s4, s4, 0x13dc0c00
	s_add_u32 s16, s10, s4
	s_addc_u32 s17, s11, 0
	s_lshl_b32 s4, s0, 15
	s_add_u32 s4, s4, 0x44c8000
	s_add_u32 s20, s8, s4
	s_addc_u32 s21, s9, 0
	s_mov_b32 s31, s0
	global_load_dwordx2 v[56:57], v2, s[12:13]
	global_load_dwordx2 v[58:59], v2, s[12:13] offset:-1024
	global_load_dword v48, v3, s[12:13] offset:1024
	global_load_dwordx2 v[60:61], v1, s[14:15] offset:0
	s_add_u32 s12, s12, 0x4000
	s_addc_u32 s13, s13, 0
	global_load_dwordx2 v[62:63], v2, s[12:13]
	global_load_dwordx2 v[64:65], v2, s[12:13] offset:-1024
	global_load_dword v49, v3, s[12:13] offset:1024
	global_load_dwordx2 v[66:67], v1, s[14:15] offset:128
	s_add_u32 s12, s12, 0x4000
	s_addc_u32 s13, s13, 0
	global_load_dwordx2 v[68:69], v2, s[12:13]
	global_load_dwordx2 v[70:71], v2, s[12:13] offset:-1024
	global_load_dword v50, v3, s[12:13] offset:1024
	global_load_dwordx2 v[72:73], v1, s[14:15] offset:256
	s_add_u32 s12, s12, 0x4000
	s_addc_u32 s13, s13, 0
	global_load_dwordx2 v[74:75], v2, s[12:13]
	global_load_dwordx2 v[76:77], v2, s[12:13] offset:-1024
	global_load_dword v51, v3, s[12:13] offset:1024
	global_load_dwordx2 v[78:79], v1, s[14:15] offset:384
	s_add_u32 s12, s12, 0x4000
	s_addc_u32 s13, s13, 0
	global_load_dwordx2 v[80:81], v2, s[12:13]
	global_load_dwordx2 v[82:83], v2, s[12:13] offset:-1024
	global_load_dword v52, v3, s[12:13] offset:1024
	global_load_dwordx2 v[84:85], v1, s[14:15] offset:512
	s_add_u32 s12, s12, 0x4000
	s_addc_u32 s13, s13, 0
	global_load_dwordx2 v[86:87], v2, s[12:13]
	global_load_dwordx2 v[88:89], v2, s[12:13] offset:-1024
	global_load_dword v53, v3, s[12:13] offset:1024
	global_load_dwordx2 v[90:91], v1, s[14:15] offset:640
	s_add_u32 s12, s12, 0x4000
	s_addc_u32 s13, s13, 0
	global_load_dwordx2 v[92:93], v2, s[12:13]
	global_load_dwordx2 v[94:95], v2, s[12:13] offset:-1024
	global_load_dword v54, v3, s[12:13] offset:1024
	global_load_dwordx2 v[96:97], v1, s[14:15] offset:768
	s_add_u32 s12, s12, 0x4000
	s_addc_u32 s13, s13, 0
	global_load_dwordx2 v[98:99], v2, s[12:13]
	global_load_dwordx2 v[100:101], v2, s[12:13] offset:-1024
	global_load_dword v55, v3, s[12:13] offset:1024
	global_load_dwordx2 v[102:103], v1, s[14:15] offset:896
	s_add_u32 s12, s12, 0x4000
	s_addc_u32 s13, s13, 0
	s_add_u32 s14, s14, 0x400
	s_addc_u32 s15, s15, 0
	v_mov_b32_e32 v6, 0
	v_mov_b32_e32 v7, 0
	v_mov_b32_e32 v8, 0
	v_mov_b32_e32 v9, 0
	v_mov_b32_e32 v10, 0
	v_mov_b32_e32 v11, 0
	v_mov_b32_e32 v12, 0
	v_mov_b32_e32 v13, 0
	v_mov_b32_e32 v14, 0
	v_mov_b32_e32 v15, 0
	v_mov_b32_e32 v16, 0
	v_mov_b32_e32 v17, 0
	v_mov_b32_e32 v41, 0
	s_mov_b32 s18, 0
	s_waitcnt vmcnt(0)
.Lml_loop:
	s_waitcnt vmcnt(35)
	v_add_f32_e32 v42, v61, v41
	v_max_f32_e32 v40, v42, v60
	v_sub_f32_e32 v43, v42, v40
	v_sub_f32_e32 v44, v60, v40
	v_mul_f32_e32 v43, s29, v43
	v_fma_f32 v44, v44, s29, v46
	v_exp_f32_e32 v38, v43
	v_exp_f32_e32 v39, v44
	v_lshlrev_b32_e32 v18, 16, v56
	v_and_b32_e32 v19, s19, v56
	v_lshlrev_b32_e32 v20, 16, v57
	v_and_b32_e32 v21, s19, v57
	v_lshlrev_b32_e32 v22, 16, v58
	v_and_b32_e32 v23, s19, v58
	v_lshlrev_b32_e32 v24, 16, v59
	v_and_b32_e32 v25, s19, v59
	v_lshlrev_b32_e32 v30, 16, v48
	v_and_b32_e32 v31, s19, v48
	v_pk_mul_f32 v[26:27], v[18:19], v[38:39] op_sel:[0,1] op_sel_hi:[1,1]
	v_pk_mul_f32 v[28:29], v[20:21], v[38:39] op_sel:[0,1] op_sel_hi:[1,1]
	v_pk_mul_f32 v[32:33], v[30:31], v[26:27] op_sel:[0,0] op_sel_hi:[1,0]
	v_pk_fma_f32 v[6:7], v[6:7], v[38:39], v[32:33] op_sel_hi:[1,0,1]
	v_pk_mul_f32 v[36:37], v[6:7], v[22:23] op_sel_hi:[1,0]
	v_pk_mul_f32 v[34:35], v[30:31], v[26:27] op_sel:[0,1] op_sel_hi:[1,1]
	v_pk_fma_f32 v[8:9], v[8:9], v[38:39], v[34:35] op_sel_hi:[1,0,1]
	v_pk_fma_f32 v[36:37], v[8:9], v[22:23], v[36:37] op_sel:[0,1,0] op_sel_hi:[1,1,1]
	v_pk_mul_f32 v[32:33], v[30:31], v[28:29] op_sel:[0,0] op_sel_hi:[1,0]
	v_pk_fma_f32 v[10:11], v[10:11], v[38:39], v[32:33] op_sel_hi:[1,0,1]
	v_pk_fma_f32 v[36:37], v[10:11], v[24:25], v[36:37] op_sel:[0,0,0] op_sel_hi:[1,0,1]
	v_pk_mul_f32 v[34:35], v[30:31], v[28:29] op_sel:[0,1] op_sel_hi:[1,1]
	v_pk_fma_f32 v[12:13], v[12:13], v[38:39], v[34:35] op_sel_hi:[1,0,1]
	v_pk_fma_f32 v[36:37], v[12:13], v[24:25], v[36:37] op_sel:[0,1,0] op_sel_hi:[1,1,1]
	v_pk_fma_f32 v[14:15], v[14:15], v[38:39], v[26:27] op_sel_hi:[1,0,1]
	v_pk_fma_f32 v[16:17], v[16:17], v[38:39], v[28:29] op_sel_hi:[1,0,1]
	v_add_f32_dpp v36, v36, v36 quad_perm:[1,0,3,2] row_mask:0xf bank_mask:0xf bound_ctrl:1
	v_add_f32_dpp v37, v37, v37 quad_perm:[1,0,3,2] row_mask:0xf bank_mask:0xf bound_ctrl:1
	s_add_u32 s16, s16, 0x1000
	v_add_f32_dpp v36, v36, v36 quad_perm:[2,3,0,1] row_mask:0xf bank_mask:0xf bound_ctrl:1
	v_add_f32_dpp v37, v37, v37 quad_perm:[2,3,0,1] row_mask:0xf bank_mask:0xf bound_ctrl:1
	s_addc_u32 s17, s17, 0
	v_add_f32_dpp v36, v36, v36 row_half_mirror row_mask:0xf bank_mask:0xf bound_ctrl:1
	v_add_f32_dpp v37, v37, v37 row_half_mirror row_mask:0xf bank_mask:0xf bound_ctrl:1
	s_cmp_eq_u32 s25, 0
	v_add_f32_dpp v36, v36, v36 row_mirror row_mask:0xf bank_mask:0xf bound_ctrl:1
	v_add_f32_dpp v37, v37, v37 row_mirror row_mask:0xf bank_mask:0xf bound_ctrl:1
	s_cbranch_scc1 .Lml_den0
.Lml_back0:
	v_cvt_pk_bf16_f32 v45, v36, v37
	global_store_dword v4, v45, s[16:17] offset:-4096
	global_load_dwordx2 v[56:57], v2, s[12:13]
	global_load_dwordx2 v[58:59], v2, s[12:13] offset:-1024
	global_load_dword v48, v3, s[12:13] offset:1024
	global_load_dwordx2 v[60:61], v1, s[14:15] offset:0
	s_add_u32 s12, s12, 0x4000
	s_addc_u32 s13, s13, 0
	s_waitcnt vmcnt(35)
	v_add_f32_e32 v42, v67, v40
	v_max_f32_e32 v41, v42, v66
	v_sub_f32_e32 v43, v42, v41
	v_sub_f32_e32 v44, v66, v41
	v_mul_f32_e32 v43, s29, v43
	v_fma_f32 v44, v44, s29, v46
	v_exp_f32_e32 v38, v43
	v_exp_f32_e32 v39, v44
	v_lshlrev_b32_e32 v18, 16, v62
	v_and_b32_e32 v19, s19, v62
	v_lshlrev_b32_e32 v20, 16, v63
	v_and_b32_e32 v21, s19, v63
	v_lshlrev_b32_e32 v22, 16, v64
	v_and_b32_e32 v23, s19, v64
	v_lshlrev_b32_e32 v24, 16, v65
	v_and_b32_e32 v25, s19, v65
	v_lshlrev_b32_e32 v30, 16, v49
	v_and_b32_e32 v31, s19, v49
	v_pk_mul_f32 v[26:27], v[18:19], v[38:39] op_sel:[0,1] op_sel_hi:[1,1]
	v_pk_mul_f32 v[28:29], v[20:21], v[38:39] op_sel:[0,1] op_sel_hi:[1,1]
	v_pk_mul_f32 v[32:33], v[30:31], v[26:27] op_sel:[0,0] op_sel_hi:[1,0]
	v_pk_fma_f32 v[6:7], v[6:7], v[38:39], v[32:33] op_sel_hi:[1,0,1]
	v_pk_mul_f32 v[36:37], v[6:7], v[22:23] op_sel_hi:[1,0]
	v_pk_mul_f32 v[34:35], v[30:31], v[26:27] op_sel:[0,1] op_sel_hi:[1,1]
	v_pk_fma_f32 v[8:9], v[8:9], v[38:39], v[34:35] op_sel_hi:[1,0,1]
	v_pk_fma_f32 v[36:37], v[8:9], v[22:23], v[36:37] op_sel:[0,1,0] op_sel_hi:[1,1,1]
	v_pk_mul_f32 v[32:33], v[30:31], v[28:29] op_sel:[0,0] op_sel_hi:[1,0]
	v_pk_fma_f32 v[10:11], v[10:11], v[38:39], v[32:33] op_sel_hi:[1,0,1]
	v_pk_fma_f32 v[36:37], v[10:11], v[24:25], v[36:37] op_sel:[0,0,0] op_sel_hi:[1,0,1]
	v_pk_mul_f32 v[34:35], v[30:31], v[28:29] op_sel:[0,1] op_sel_hi:[1,1]
	v_pk_fma_f32 v[12:13], v[12:13], v[38:39], v[34:35] op_sel_hi:[1,0,1]
	v_pk_fma_f32 v[36:37], v[12:13], v[24:25], v[36:37] op_sel:[0,1,0] op_sel_hi:[1,1,1]
	v_pk_fma_f32 v[14:15], v[14:15], v[38:39], v[26:27] op_sel_hi:[1,0,1]
	v_pk_fma_f32 v[16:17], v[16:17], v[38:39], v[28:29] op_sel_hi:[1,0,1]
	v_add_f32_dpp v36, v36, v36 quad_perm:[1,0,3,2] row_mask:0xf bank_mask:0xf bound_ctrl:1
	v_add_f32_dpp v37, v37, v37 quad_perm:[1,0,3,2] row_mask:0xf bank_mask:0xf bound_ctrl:1
	s_add_u32 s16, s16, 0x1000
	v_add_f32_dpp v36, v36, v36 quad_perm:[2,3,0,1] row_mask:0xf bank_mask:0xf bound_ctrl:1
	v_add_f32_dpp v37, v37, v37 quad_perm:[2,3,0,1] row_mask:0xf bank_mask:0xf bound_ctrl:1
	s_addc_u32 s17, s17, 0
	v_add_f32_dpp v36, v36, v36 row_half_mirror row_mask:0xf bank_mask:0xf bound_ctrl:1
	v_add_f32_dpp v37, v37, v37 row_half_mirror row_mask:0xf bank_mask:0xf bound_ctrl:1
	s_cmp_eq_u32 s25, 1
	v_add_f32_dpp v36, v36, v36 row_mirror row_mask:0xf bank_mask:0xf bound_ctrl:1
	v_add_f32_dpp v37, v37, v37 row_mirror row_mask:0xf bank_mask:0xf bound_ctrl:1
	s_cbranch_scc1 .Lml_den1
.Lml_back1:
	v_cvt_pk_bf16_f32 v45, v36, v37
	global_store_dword v4, v45, s[16:17] offset:-4096
	global_load_dwordx2 v[62:63], v2, s[12:13]
	global_load_dwordx2 v[64:65], v2, s[12:13] offset:-1024
	global_load_dword v49, v3, s[12:13] offset:1024
	global_load_dwordx2 v[66:67], v1, s[14:15] offset:128
	s_add_u32 s12, s12, 0x4000
	s_addc_u32 s13, s13, 0
	s_waitcnt vmcnt(35)
	v_add_f32_e32 v42, v73, v41
	v_max_f32_e32 v40, v42, v72
	v_sub_f32_e32 v43, v42, v40
	v_sub_f32_e32 v44, v72, v40
	v_mul_f32_e32 v43, s29, v43
	v_fma_f32 v44, v44, s29, v46
	v_exp_f32_e32 v38, v43
	v_exp_f32_e32 v39, v44
	v_lshlrev_b32_e32 v18, 16, v68
	v_and_b32_e32 v19, s19, v68
	v_lshlrev_b32_e32 v20, 16, v69
	v_and_b32_e32 v21, s19, v69
	v_lshlrev_b32_e32 v22, 16, v70
	v_and_b32_e32 v23, s19, v70
	v_lshlrev_b32_e32 v24, 16, v71
	v_and_b32_e32 v25, s19, v71
	v_lshlrev_b32_e32 v30, 16, v50
	v_and_b32_e32 v31, s19, v50
	v_pk_mul_f32 v[26:27], v[18:19], v[38:39] op_sel:[0,1] op_sel_hi:[1,1]
	v_pk_mul_f32 v[28:29], v[20:21], v[38:39] op_sel:[0,1] op_sel_hi:[1,1]
	v_pk_mul_f32 v[32:33], v[30:31], v[26:27] op_sel:[0,0] op_sel_hi:[1,0]
	v_pk_fma_f32 v[6:7], v[6:7], v[38:39], v[32:33] op_sel_hi:[1,0,1]
	v_pk_mul_f32 v[36:37], v[6:7], v[22:23] op_sel_hi:[1,0]
	v_pk_mul_f32 v[34:35], v[30:31], v[26:27] op_sel:[0,1] op_sel_hi:[1,1]
	v_pk_fma_f32 v[8:9], v[8:9], v[38:39], v[34:35] op_sel_hi:[1,0,1]
	v_pk_fma_f32 v[36:37], v[8:9], v[22:23], v[36:37] op_sel:[0,1,0] op_sel_hi:[1,1,1]
	v_pk_mul_f32 v[32:33], v[30:31], v[28:29] op_sel:[0,0] op_sel_hi:[1,0]
	v_pk_fma_f32 v[10:11], v[10:11], v[38:39], v[32:33] op_sel_hi:[1,0,1]
	v_pk_fma_f32 v[36:37], v[10:11], v[24:25], v[36:37] op_sel:[0,0,0] op_sel_hi:[1,0,1]
	v_pk_mul_f32 v[34:35], v[30:31], v[28:29] op_sel:[0,1] op_sel_hi:[1,1]
	v_pk_fma_f32 v[12:13], v[12:13], v[38:39], v[34:35] op_sel_hi:[1,0,1]
	v_pk_fma_f32 v[36:37], v[12:13], v[24:25], v[36:37] op_sel:[0,1,0] op_sel_hi:[1,1,1]
	v_pk_fma_f32 v[14:15], v[14:15], v[38:39], v[26:27] op_sel_hi:[1,0,1]
	v_pk_fma_f32 v[16:17], v[16:17], v[38:39], v[28:29] op_sel_hi:[1,0,1]
	v_add_f32_dpp v36, v36, v36 quad_perm:[1,0,3,2] row_mask:0xf bank_mask:0xf bound_ctrl:1
	v_add_f32_dpp v37, v37, v37 quad_perm:[1,0,3,2] row_mask:0xf bank_mask:0xf bound_ctrl:1
	s_add_u32 s16, s16, 0x1000
	v_add_f32_dpp v36, v36, v36 quad_perm:[2,3,0,1] row_mask:0xf bank_mask:0xf bound_ctrl:1
	v_add_f32_dpp v37, v37, v37 quad_perm:[2,3,0,1] row_mask:0xf bank_mask:0xf bound_ctrl:1
	s_addc_u32 s17, s17, 0
	v_add_f32_dpp v36, v36, v36 row_half_mirror row_mask:0xf bank_mask:0xf bound_ctrl:1
	v_add_f32_dpp v37, v37, v37 row_half_mirror row_mask:0xf bank_mask:0xf bound_ctrl:1
	s_cmp_eq_u32 s25, 2
	v_add_f32_dpp v36, v36, v36 row_mirror row_mask:0xf bank_mask:0xf bound_ctrl:1
	v_add_f32_dpp v37, v37, v37 row_mirror row_mask:0xf bank_mask:0xf bound_ctrl:1
	s_cbranch_scc1 .Lml_den2
.Lml_back2:
	v_cvt_pk_bf16_f32 v45, v36, v37
	global_store_dword v4, v45, s[16:17] offset:-4096
	global_load_dwordx2 v[68:69], v2, s[12:13]
	global_load_dwordx2 v[70:71], v2, s[12:13] offset:-1024
	global_load_dword v50, v3, s[12:13] offset:1024
	global_load_dwordx2 v[72:73], v1, s[14:15] offset:256
	s_add_u32 s12, s12, 0x4000
	s_addc_u32 s13, s13, 0
	s_waitcnt vmcnt(35)
	v_add_f32_e32 v42, v79, v40
	v_max_f32_e32 v41, v42, v78
	v_sub_f32_e32 v43, v42, v41
	v_sub_f32_e32 v44, v78, v41
	v_mul_f32_e32 v43, s29, v43
	v_fma_f32 v44, v44, s29, v46
	v_exp_f32_e32 v38, v43
	v_exp_f32_e32 v39, v44
	v_lshlrev_b32_e32 v18, 16, v74
	v_and_b32_e32 v19, s19, v74
	v_lshlrev_b32_e32 v20, 16, v75
	v_and_b32_e32 v21, s19, v75
	v_lshlrev_b32_e32 v22, 16, v76
	v_and_b32_e32 v23, s19, v76
	v_lshlrev_b32_e32 v24, 16, v77
	v_and_b32_e32 v25, s19, v77
	v_lshlrev_b32_e32 v30, 16, v51
	v_and_b32_e32 v31, s19, v51
	v_pk_mul_f32 v[26:27], v[18:19], v[38:39] op_sel:[0,1] op_sel_hi:[1,1]
	v_pk_mul_f32 v[28:29], v[20:21], v[38:39] op_sel:[0,1] op_sel_hi:[1,1]
	v_pk_mul_f32 v[32:33], v[30:31], v[26:27] op_sel:[0,0] op_sel_hi:[1,0]
	v_pk_fma_f32 v[6:7], v[6:7], v[38:39], v[32:33] op_sel_hi:[1,0,1]
	v_pk_mul_f32 v[36:37], v[6:7], v[22:23] op_sel_hi:[1,0]
	v_pk_mul_f32 v[34:35], v[30:31], v[26:27] op_sel:[0,1] op_sel_hi:[1,1]
	v_pk_fma_f32 v[8:9], v[8:9], v[38:39], v[34:35] op_sel_hi:[1,0,1]
	v_pk_fma_f32 v[36:37], v[8:9], v[22:23], v[36:37] op_sel:[0,1,0] op_sel_hi:[1,1,1]
	v_pk_mul_f32 v[32:33], v[30:31], v[28:29] op_sel:[0,0] op_sel_hi:[1,0]
	v_pk_fma_f32 v[10:11], v[10:11], v[38:39], v[32:33] op_sel_hi:[1,0,1]
	v_pk_fma_f32 v[36:37], v[10:11], v[24:25], v[36:37] op_sel:[0,0,0] op_sel_hi:[1,0,1]
	v_pk_mul_f32 v[34:35], v[30:31], v[28:29] op_sel:[0,1] op_sel_hi:[1,1]
	v_pk_fma_f32 v[12:13], v[12:13], v[38:39], v[34:35] op_sel_hi:[1,0,1]
	v_pk_fma_f32 v[36:37], v[12:13], v[24:25], v[36:37] op_sel:[0,1,0] op_sel_hi:[1,1,1]
	v_pk_fma_f32 v[14:15], v[14:15], v[38:39], v[26:27] op_sel_hi:[1,0,1]
	v_pk_fma_f32 v[16:17], v[16:17], v[38:39], v[28:29] op_sel_hi:[1,0,1]
	v_add_f32_dpp v36, v36, v36 quad_perm:[1,0,3,2] row_mask:0xf bank_mask:0xf bound_ctrl:1
	v_add_f32_dpp v37, v37, v37 quad_perm:[1,0,3,2] row_mask:0xf bank_mask:0xf bound_ctrl:1
	s_add_u32 s16, s16, 0x1000
	v_add_f32_dpp v36, v36, v36 quad_perm:[2,3,0,1] row_mask:0xf bank_mask:0xf bound_ctrl:1
	v_add_f32_dpp v37, v37, v37 quad_perm:[2,3,0,1] row_mask:0xf bank_mask:0xf bound_ctrl:1
	s_addc_u32 s17, s17, 0
	v_add_f32_dpp v36, v36, v36 row_half_mirror row_mask:0xf bank_mask:0xf bound_ctrl:1
	v_add_f32_dpp v37, v37, v37 row_half_mirror row_mask:0xf bank_mask:0xf bound_ctrl:1
	s_cmp_eq_u32 s25, 3
	v_add_f32_dpp v36, v36, v36 row_mirror row_mask:0xf bank_mask:0xf bound_ctrl:1
	v_add_f32_dpp v37, v37, v37 row_mirror row_mask:0xf bank_mask:0xf bound_ctrl:1
	s_cbranch_scc1 .Lml_den3
.Lml_back3:
	v_cvt_pk_bf16_f32 v45, v36, v37
	global_store_dword v4, v45, s[16:17] offset:-4096
	global_load_dwordx2 v[74:75], v2, s[12:13]
	global_load_dwordx2 v[76:77], v2, s[12:13] offset:-1024
	global_load_dword v51, v3, s[12:13] offset:1024
	global_load_dwordx2 v[78:79], v1, s[14:15] offset:384
	s_add_u32 s12, s12, 0x4000
	s_addc_u32 s13, s13, 0
	s_waitcnt vmcnt(35)
	v_add_f32_e32 v42, v85, v41
	v_max_f32_e32 v40, v42, v84
	v_sub_f32_e32 v43, v42, v40
	v_sub_f32_e32 v44, v84, v40
	v_mul_f32_e32 v43, s29, v43
	v_fma_f32 v44, v44, s29, v46
	v_exp_f32_e32 v38, v43
	v_exp_f32_e32 v39, v44
	v_lshlrev_b32_e32 v18, 16, v80
	v_and_b32_e32 v19, s19, v80
	v_lshlrev_b32_e32 v20, 16, v81
	v_and_b32_e32 v21, s19, v81
	v_lshlrev_b32_e32 v22, 16, v82
	v_and_b32_e32 v23, s19, v82
	v_lshlrev_b32_e32 v24, 16, v83
	v_and_b32_e32 v25, s19, v83
	v_lshlrev_b32_e32 v30, 16, v52
	v_and_b32_e32 v31, s19, v52
	v_pk_mul_f32 v[26:27], v[18:19], v[38:39] op_sel:[0,1] op_sel_hi:[1,1]
	v_pk_mul_f32 v[28:29], v[20:21], v[38:39] op_sel:[0,1] op_sel_hi:[1,1]
	v_pk_mul_f32 v[32:33], v[30:31], v[26:27] op_sel:[0,0] op_sel_hi:[1,0]
	v_pk_fma_f32 v[6:7], v[6:7], v[38:39], v[32:33] op_sel_hi:[1,0,1]
	v_pk_mul_f32 v[36:37], v[6:7], v[22:23] op_sel_hi:[1,0]
	v_pk_mul_f32 v[34:35], v[30:31], v[26:27] op_sel:[0,1] op_sel_hi:[1,1]
	v_pk_fma_f32 v[8:9], v[8:9], v[38:39], v[34:35] op_sel_hi:[1,0,1]
	v_pk_fma_f32 v[36:37], v[8:9], v[22:23], v[36:37] op_sel:[0,1,0] op_sel_hi:[1,1,1]
	v_pk_mul_f32 v[32:33], v[30:31], v[28:29] op_sel:[0,0] op_sel_hi:[1,0]
	v_pk_fma_f32 v[10:11], v[10:11], v[38:39], v[32:33] op_sel_hi:[1,0,1]
	v_pk_fma_f32 v[36:37], v[10:11], v[24:25], v[36:37] op_sel:[0,0,0] op_sel_hi:[1,0,1]
	v_pk_mul_f32 v[34:35], v[30:31], v[28:29] op_sel:[0,1] op_sel_hi:[1,1]
	v_pk_fma_f32 v[12:13], v[12:13], v[38:39], v[34:35] op_sel_hi:[1,0,1]
	v_pk_fma_f32 v[36:37], v[12:13], v[24:25], v[36:37] op_sel:[0,1,0] op_sel_hi:[1,1,1]
	v_pk_fma_f32 v[14:15], v[14:15], v[38:39], v[26:27] op_sel_hi:[1,0,1]
	v_pk_fma_f32 v[16:17], v[16:17], v[38:39], v[28:29] op_sel_hi:[1,0,1]
	v_add_f32_dpp v36, v36, v36 quad_perm:[1,0,3,2] row_mask:0xf bank_mask:0xf bound_ctrl:1
	v_add_f32_dpp v37, v37, v37 quad_perm:[1,0,3,2] row_mask:0xf bank_mask:0xf bound_ctrl:1
	s_add_u32 s16, s16, 0x1000
	v_add_f32_dpp v36, v36, v36 quad_perm:[2,3,0,1] row_mask:0xf bank_mask:0xf bound_ctrl:1
	v_add_f32_dpp v37, v37, v37 quad_perm:[2,3,0,1] row_mask:0xf bank_mask:0xf bound_ctrl:1
	s_addc_u32 s17, s17, 0
	v_add_f32_dpp v36, v36, v36 row_half_mirror row_mask:0xf bank_mask:0xf bound_ctrl:1
	v_add_f32_dpp v37, v37, v37 row_half_mirror row_mask:0xf bank_mask:0xf bound_ctrl:1
	s_cmp_eq_u32 s25, 4
	v_add_f32_dpp v36, v36, v36 row_mirror row_mask:0xf bank_mask:0xf bound_ctrl:1
	v_add_f32_dpp v37, v37, v37 row_mirror row_mask:0xf bank_mask:0xf bound_ctrl:1
	s_cbranch_scc1 .Lml_den4
.Lml_back4:
	v_cvt_pk_bf16_f32 v45, v36, v37
	global_store_dword v4, v45, s[16:17] offset:-4096
	global_load_dwordx2 v[80:81], v2, s[12:13]
	global_load_dwordx2 v[82:83], v2, s[12:13] offset:-1024
	global_load_dword v52, v3, s[12:13] offset:1024
	global_load_dwordx2 v[84:85], v1, s[14:15] offset:512
	s_add_u32 s12, s12, 0x4000
	s_addc_u32 s13, s13, 0
	s_waitcnt vmcnt(35)
	v_add_f32_e32 v42, v91, v40
	v_max_f32_e32 v41, v42, v90
	v_sub_f32_e32 v43, v42, v41
	v_sub_f32_e32 v44, v90, v41
	v_mul_f32_e32 v43, s29, v43
	v_fma_f32 v44, v44, s29, v46
	v_exp_f32_e32 v38, v43
	v_exp_f32_e32 v39, v44
	v_lshlrev_b32_e32 v18, 16, v86
	v_and_b32_e32 v19, s19, v86
	v_lshlrev_b32_e32 v20, 16, v87
	v_and_b32_e32 v21, s19, v87
	v_lshlrev_b32_e32 v22, 16, v88
	v_and_b32_e32 v23, s19, v88
	v_lshlrev_b32_e32 v24, 16, v89
	v_and_b32_e32 v25, s19, v89
	v_lshlrev_b32_e32 v30, 16, v53
	v_and_b32_e32 v31, s19, v53
	v_pk_mul_f32 v[26:27], v[18:19], v[38:39] op_sel:[0,1] op_sel_hi:[1,1]
	v_pk_mul_f32 v[28:29], v[20:21], v[38:39] op_sel:[0,1] op_sel_hi:[1,1]
	v_pk_mul_f32 v[32:33], v[30:31], v[26:27] op_sel:[0,0] op_sel_hi:[1,0]
	v_pk_fma_f32 v[6:7], v[6:7], v[38:39], v[32:33] op_sel_hi:[1,0,1]
	v_pk_mul_f32 v[36:37], v[6:7], v[22:23] op_sel_hi:[1,0]
	v_pk_mul_f32 v[34:35], v[30:31], v[26:27] op_sel:[0,1] op_sel_hi:[1,1]
	v_pk_fma_f32 v[8:9], v[8:9], v[38:39], v[34:35] op_sel_hi:[1,0,1]
	v_pk_fma_f32 v[36:37], v[8:9], v[22:23], v[36:37] op_sel:[0,1,0] op_sel_hi:[1,1,1]
	v_pk_mul_f32 v[32:33], v[30:31], v[28:29] op_sel:[0,0] op_sel_hi:[1,0]
	v_pk_fma_f32 v[10:11], v[10:11], v[38:39], v[32:33] op_sel_hi:[1,0,1]
	v_pk_fma_f32 v[36:37], v[10:11], v[24:25], v[36:37] op_sel:[0,0,0] op_sel_hi:[1,0,1]
	v_pk_mul_f32 v[34:35], v[30:31], v[28:29] op_sel:[0,1] op_sel_hi:[1,1]
	v_pk_fma_f32 v[12:13], v[12:13], v[38:39], v[34:35] op_sel_hi:[1,0,1]
	v_pk_fma_f32 v[36:37], v[12:13], v[24:25], v[36:37] op_sel:[0,1,0] op_sel_hi:[1,1,1]
	v_pk_fma_f32 v[14:15], v[14:15], v[38:39], v[26:27] op_sel_hi:[1,0,1]
	v_pk_fma_f32 v[16:17], v[16:17], v[38:39], v[28:29] op_sel_hi:[1,0,1]
	v_add_f32_dpp v36, v36, v36 quad_perm:[1,0,3,2] row_mask:0xf bank_mask:0xf bound_ctrl:1
	v_add_f32_dpp v37, v37, v37 quad_perm:[1,0,3,2] row_mask:0xf bank_mask:0xf bound_ctrl:1
	s_add_u32 s16, s16, 0x1000
	v_add_f32_dpp v36, v36, v36 quad_perm:[2,3,0,1] row_mask:0xf bank_mask:0xf bound_ctrl:1
	v_add_f32_dpp v37, v37, v37 quad_perm:[2,3,0,1] row_mask:0xf bank_mask:0xf bound_ctrl:1
	s_addc_u32 s17, s17, 0
	v_add_f32_dpp v36, v36, v36 row_half_mirror row_mask:0xf bank_mask:0xf bound_ctrl:1
	v_add_f32_dpp v37, v37, v37 row_half_mirror row_mask:0xf bank_mask:0xf bound_ctrl:1
	s_cmp_eq_u32 s25, 5
	v_add_f32_dpp v36, v36, v36 row_mirror row_mask:0xf bank_mask:0xf bound_ctrl:1
	v_add_f32_dpp v37, v37, v37 row_mirror row_mask:0xf bank_mask:0xf bound_ctrl:1
	s_cbranch_scc1 .Lml_den5
.Lml_back5:
	v_cvt_pk_bf16_f32 v45, v36, v37
	global_store_dword v4, v45, s[16:17] offset:-4096
	global_load_dwordx2 v[86:87], v2, s[12:13]
	global_load_dwordx2 v[88:89], v2, s[12:13] offset:-1024
	global_load_dword v53, v3, s[12:13] offset:1024
	global_load_dwordx2 v[90:91], v1, s[14:15] offset:640
	s_add_u32 s12, s12, 0x4000
	s_addc_u32 s13, s13, 0
	s_waitcnt vmcnt(35)
	v_add_f32_e32 v42, v97, v41
	v_max_f32_e32 v40, v42, v96
	v_sub_f32_e32 v43, v42, v40
	v_sub_f32_e32 v44, v96, v40
	v_mul_f32_e32 v43, s29, v43
	v_fma_f32 v44, v44, s29, v46
	v_exp_f32_e32 v38, v43
	v_exp_f32_e32 v39, v44
	v_lshlrev_b32_e32 v18, 16, v92
	v_and_b32_e32 v19, s19, v92
	v_lshlrev_b32_e32 v20, 16, v93
	v_and_b32_e32 v21, s19, v93
	v_lshlrev_b32_e32 v22, 16, v94
	v_and_b32_e32 v23, s19, v94
	v_lshlrev_b32_e32 v24, 16, v95
	v_and_b32_e32 v25, s19, v95
	v_lshlrev_b32_e32 v30, 16, v54
	v_and_b32_e32 v31, s19, v54
	v_pk_mul_f32 v[26:27], v[18:19], v[38:39] op_sel:[0,1] op_sel_hi:[1,1]
	v_pk_mul_f32 v[28:29], v[20:21], v[38:39] op_sel:[0,1] op_sel_hi:[1,1]
	v_pk_mul_f32 v[32:33], v[30:31], v[26:27] op_sel:[0,0] op_sel_hi:[1,0]
	v_pk_fma_f32 v[6:7], v[6:7], v[38:39], v[32:33] op_sel_hi:[1,0,1]
	v_pk_mul_f32 v[36:37], v[6:7], v[22:23] op_sel_hi:[1,0]
	v_pk_mul_f32 v[34:35], v[30:31], v[26:27] op_sel:[0,1] op_sel_hi:[1,1]
	v_pk_fma_f32 v[8:9], v[8:9], v[38:39], v[34:35] op_sel_hi:[1,0,1]
	v_pk_fma_f32 v[36:37], v[8:9], v[22:23], v[36:37] op_sel:[0,1,0] op_sel_hi:[1,1,1]
	v_pk_mul_f32 v[32:33], v[30:31], v[28:29] op_sel:[0,0] op_sel_hi:[1,0]
	v_pk_fma_f32 v[10:11], v[10:11], v[38:39], v[32:33] op_sel_hi:[1,0,1]
	v_pk_fma_f32 v[36:37], v[10:11], v[24:25], v[36:37] op_sel:[0,0,0] op_sel_hi:[1,0,1]
	v_pk_mul_f32 v[34:35], v[30:31], v[28:29] op_sel:[0,1] op_sel_hi:[1,1]
	v_pk_fma_f32 v[12:13], v[12:13], v[38:39], v[34:35] op_sel_hi:[1,0,1]
	v_pk_fma_f32 v[36:37], v[12:13], v[24:25], v[36:37] op_sel:[0,1,0] op_sel_hi:[1,1,1]
	v_pk_fma_f32 v[14:15], v[14:15], v[38:39], v[26:27] op_sel_hi:[1,0,1]
	v_pk_fma_f32 v[16:17], v[16:17], v[38:39], v[28:29] op_sel_hi:[1,0,1]
	v_add_f32_dpp v36, v36, v36 quad_perm:[1,0,3,2] row_mask:0xf bank_mask:0xf bound_ctrl:1
	v_add_f32_dpp v37, v37, v37 quad_perm:[1,0,3,2] row_mask:0xf bank_mask:0xf bound_ctrl:1
	s_add_u32 s16, s16, 0x1000
	v_add_f32_dpp v36, v36, v36 quad_perm:[2,3,0,1] row_mask:0xf bank_mask:0xf bound_ctrl:1
	v_add_f32_dpp v37, v37, v37 quad_perm:[2,3,0,1] row_mask:0xf bank_mask:0xf bound_ctrl:1
	s_addc_u32 s17, s17, 0
	v_add_f32_dpp v36, v36, v36 row_half_mirror row_mask:0xf bank_mask:0xf bound_ctrl:1
	v_add_f32_dpp v37, v37, v37 row_half_mirror row_mask:0xf bank_mask:0xf bound_ctrl:1
	s_cmp_eq_u32 s25, 6
	v_add_f32_dpp v36, v36, v36 row_mirror row_mask:0xf bank_mask:0xf bound_ctrl:1
	v_add_f32_dpp v37, v37, v37 row_mirror row_mask:0xf bank_mask:0xf bound_ctrl:1
	s_cbranch_scc1 .Lml_den6
.Lml_back6:
	v_cvt_pk_bf16_f32 v45, v36, v37
	global_store_dword v4, v45, s[16:17] offset:-4096
	global_load_dwordx2 v[92:93], v2, s[12:13]
	global_load_dwordx2 v[94:95], v2, s[12:13] offset:-1024
	global_load_dword v54, v3, s[12:13] offset:1024
	global_load_dwordx2 v[96:97], v1, s[14:15] offset:768
	s_add_u32 s12, s12, 0x4000
	s_addc_u32 s13, s13, 0
	s_waitcnt vmcnt(35)
	v_add_f32_e32 v42, v103, v40
	v_max_f32_e32 v41, v42, v102
	v_sub_f32_e32 v43, v42, v41
	v_sub_f32_e32 v44, v102, v41
	v_mul_f32_e32 v43, s29, v43
	v_fma_f32 v44, v44, s29, v46
	v_exp_f32_e32 v38, v43
	v_exp_f32_e32 v39, v44
	v_lshlrev_b32_e32 v18, 16, v98
	v_and_b32_e32 v19, s19, v98
	v_lshlrev_b32_e32 v20, 16, v99
	v_and_b32_e32 v21, s19, v99
	v_lshlrev_b32_e32 v22, 16, v100
	v_and_b32_e32 v23, s19, v100
	v_lshlrev_b32_e32 v24, 16, v101
	v_and_b32_e32 v25, s19, v101
	v_lshlrev_b32_e32 v30, 16, v55
	v_and_b32_e32 v31, s19, v55
	v_pk_mul_f32 v[26:27], v[18:19], v[38:39] op_sel:[0,1] op_sel_hi:[1,1]
	v_pk_mul_f32 v[28:29], v[20:21], v[38:39] op_sel:[0,1] op_sel_hi:[1,1]
	v_pk_mul_f32 v[32:33], v[30:31], v[26:27] op_sel:[0,0] op_sel_hi:[1,0]
	v_pk_fma_f32 v[6:7], v[6:7], v[38:39], v[32:33] op_sel_hi:[1,0,1]
	v_pk_mul_f32 v[36:37], v[6:7], v[22:23] op_sel_hi:[1,0]
	v_pk_mul_f32 v[34:35], v[30:31], v[26:27] op_sel:[0,1] op_sel_hi:[1,1]
	v_pk_fma_f32 v[8:9], v[8:9], v[38:39], v[34:35] op_sel_hi:[1,0,1]
	v_pk_fma_f32 v[36:37], v[8:9], v[22:23], v[36:37] op_sel:[0,1,0] op_sel_hi:[1,1,1]
	v_pk_mul_f32 v[32:33], v[30:31], v[28:29] op_sel:[0,0] op_sel_hi:[1,0]
	v_pk_fma_f32 v[10:11], v[10:11], v[38:39], v[32:33] op_sel_hi:[1,0,1]
	v_pk_fma_f32 v[36:37], v[10:11], v[24:25], v[36:37] op_sel:[0,0,0] op_sel_hi:[1,0,1]
	v_pk_mul_f32 v[34:35], v[30:31], v[28:29] op_sel:[0,1] op_sel_hi:[1,1]
	v_pk_fma_f32 v[12:13], v[12:13], v[38:39], v[34:35] op_sel_hi:[1,0,1]
	v_pk_fma_f32 v[36:37], v[12:13], v[24:25], v[36:37] op_sel:[0,1,0] op_sel_hi:[1,1,1]
	v_pk_fma_f32 v[14:15], v[14:15], v[38:39], v[26:27] op_sel_hi:[1,0,1]
	v_pk_fma_f32 v[16:17], v[16:17], v[38:39], v[28:29] op_sel_hi:[1,0,1]
	v_add_f32_dpp v36, v36, v36 quad_perm:[1,0,3,2] row_mask:0xf bank_mask:0xf bound_ctrl:1
	v_add_f32_dpp v37, v37, v37 quad_perm:[1,0,3,2] row_mask:0xf bank_mask:0xf bound_ctrl:1
	s_add_u32 s16, s16, 0x1000
	v_add_f32_dpp v36, v36, v36 quad_perm:[2,3,0,1] row_mask:0xf bank_mask:0xf bound_ctrl:1
	v_add_f32_dpp v37, v37, v37 quad_perm:[2,3,0,1] row_mask:0xf bank_mask:0xf bound_ctrl:1
	s_addc_u32 s17, s17, 0
	v_add_f32_dpp v36, v36, v36 row_half_mirror row_mask:0xf bank_mask:0xf bound_ctrl:1
	v_add_f32_dpp v37, v37, v37 row_half_mirror row_mask:0xf bank_mask:0xf bound_ctrl:1
	s_cmp_eq_u32 s25, 7
	v_add_f32_dpp v36, v36, v36 row_mirror row_mask:0xf bank_mask:0xf bound_ctrl:1
	v_add_f32_dpp v37, v37, v37 row_mirror row_mask:0xf bank_mask:0xf bound_ctrl:1
	s_cbranch_scc1 .Lml_den7
.Lml_back7:
	v_cvt_pk_bf16_f32 v45, v36, v37
	global_store_dword v4, v45, s[16:17] offset:-4096
	global_load_dwordx2 v[98:99], v2, s[12:13]
	global_load_dwordx2 v[100:101], v2, s[12:13] offset:-1024
	global_load_dword v55, v3, s[12:13] offset:1024
	global_load_dwordx2 v[102:103], v1, s[14:15] offset:896
	s_add_u32 s12, s12, 0x4000
	s_addc_u32 s13, s13, 0
	s_add_u32 s14, s14, 0x400
	s_addc_u32 s15, s15, 0
	s_add_u32 s22, s22, 0x400
	s_addc_u32 s23, s23, 0
	s_sub_i32 s25, s25, 8
	s_add_i32 s18, s18, 8
	s_cmpk_lt_u32 s18, 0x800
	s_cbranch_scc1 .Lml_loop
	global_store_dwordx2 v47, v[6:7], s[20:21] offset:0
	global_store_dwordx2 v47, v[8:9], s[20:21] offset:512
	global_store_dwordx2 v47, v[10:11], s[20:21] offset:1024
	global_store_dwordx2 v47, v[12:13], s[20:21] offset:1536
	s_cmp_lg_u32 s24, 0
	s_cbranch_scc1 .Lml_nonm
	s_lshl_b32 s4, s31, 8
	s_add_u32 s4, s4, 0x46c8000
	s_add_u32 s0, s8, s4
	s_addc_u32 s1, s9, 0
	global_store_dwordx2 v105, v[14:15], s[0:1]
	global_store_dwordx2 v105, v[16:17], s[0:1] offset:8
	s_lshl_b32 s4, s31, 2
	s_add_u32 s4, s4, 0x46cc000
	s_add_u32 s0, s8, s4
	s_addc_u32 s1, s9, 0
	global_store_dword v1, v41, s[0:1]
.Lml_nonm:
	s_add_i32 s30, s30, s28
	s_waitcnt vmcnt(0)
	s_cmpk_lt_i32 s30, 0x400
	s_cbranch_scc1 .Lml_item
	s_branch .LBB0_185
.Lml_den0:
	v_pk_mul_f32 v[32:33], v[14:15], v[22:23]
	v_pk_fma_f32 v[32:33], v[16:17], v[24:25], v[32:33]
	v_mul_f32_e32 v34, 0xbfb8aa3b, v40
	v_add_f32_e32 v32, v32, v33
	v_exp_f32_e32 v34, v34
	s_nop 1
	v_add_f32_dpp v32, v32, v32 quad_perm:[1,0,3,2] row_mask:0xf bank_mask:0xf bound_ctrl:1
	s_nop 1
	v_add_f32_dpp v32, v32, v32 quad_perm:[2,3,0,1] row_mask:0xf bank_mask:0xf bound_ctrl:1
	s_nop 1
	v_add_f32_dpp v32, v32, v32 row_half_mirror row_mask:0xf bank_mask:0xf bound_ctrl:1
	s_nop 1
	v_add_f32_dpp v32, v32, v32 row_mirror row_mask:0xf bank_mask:0xf bound_ctrl:1
	v_max_f32_e64 v32, |v32|, v34
	v_rcp_f32_e32 v32, v32
	s_add_i32 s25, s25, 16
	global_store_dword v1, v32, s[22:23] offset:8
	s_branch .Lml_back0
.Lml_den1:
	v_pk_mul_f32 v[32:33], v[14:15], v[22:23]
	v_pk_fma_f32 v[32:33], v[16:17], v[24:25], v[32:33]
	v_mul_f32_e32 v34, 0xbfb8aa3b, v41
	v_add_f32_e32 v32, v32, v33
	v_exp_f32_e32 v34, v34
	s_nop 1
	v_add_f32_dpp v32, v32, v32 quad_perm:[1,0,3,2] row_mask:0xf bank_mask:0xf bound_ctrl:1
	s_nop 1
	v_add_f32_dpp v32, v32, v32 quad_perm:[2,3,0,1] row_mask:0xf bank_mask:0xf bound_ctrl:1
	s_nop 1
	v_add_f32_dpp v32, v32, v32 row_half_mirror row_mask:0xf bank_mask:0xf bound_ctrl:1
	s_nop 1
	v_add_f32_dpp v32, v32, v32 row_mirror row_mask:0xf bank_mask:0xf bound_ctrl:1
	v_max_f32_e64 v32, |v32|, v34
	v_rcp_f32_e32 v32, v32
	s_add_i32 s25, s25, 16
	global_store_dword v1, v32, s[22:23] offset:136
	s_branch .Lml_back1
.Lml_den2:
	v_pk_mul_f32 v[32:33], v[14:15], v[22:23]
	v_pk_fma_f32 v[32:33], v[16:17], v[24:25], v[32:33]
	v_mul_f32_e32 v34, 0xbfb8aa3b, v40
	v_add_f32_e32 v32, v32, v33
	v_exp_f32_e32 v34, v34
	s_nop 1
	v_add_f32_dpp v32, v32, v32 quad_perm:[1,0,3,2] row_mask:0xf bank_mask:0xf bound_ctrl:1
	s_nop 1
	v_add_f32_dpp v32, v32, v32 quad_perm:[2,3,0,1] row_mask:0xf bank_mask:0xf bound_ctrl:1
	s_nop 1
	v_add_f32_dpp v32, v32, v32 row_half_mirror row_mask:0xf bank_mask:0xf bound_ctrl:1
	s_nop 1
	v_add_f32_dpp v32, v32, v32 row_mirror row_mask:0xf bank_mask:0xf bound_ctrl:1
	v_max_f32_e64 v32, |v32|, v34
	v_rcp_f32_e32 v32, v32
	s_add_i32 s25, s25, 16
	global_store_dword v1, v32, s[22:23] offset:264
	s_branch .Lml_back2
.Lml_den3:
	v_pk_mul_f32 v[32:33], v[14:15], v[22:23]
	v_pk_fma_f32 v[32:33], v[16:17], v[24:25], v[32:33]
	v_mul_f32_e32 v34, 0xbfb8aa3b, v41
	v_add_f32_e32 v32, v32, v33
	v_exp_f32_e32 v34, v34
	s_nop 1
	v_add_f32_dpp v32, v32, v32 quad_perm:[1,0,3,2] row_mask:0xf bank_mask:0xf bound_ctrl:1
	s_nop 1
	v_add_f32_dpp v32, v32, v32 quad_perm:[2,3,0,1] row_mask:0xf bank_mask:0xf bound_ctrl:1
	s_nop 1
	v_add_f32_dpp v32, v32, v32 row_half_mirror row_mask:0xf bank_mask:0xf bound_ctrl:1
	s_nop 1
	v_add_f32_dpp v32, v32, v32 row_mirror row_mask:0xf bank_mask:0xf bound_ctrl:1
	v_max_f32_e64 v32, |v32|, v34
	v_rcp_f32_e32 v32, v32
	s_add_i32 s25, s25, 16
	global_store_dword v1, v32, s[22:23] offset:392
	s_branch .Lml_back3
.Lml_den4:
	v_pk_mul_f32 v[32:33], v[14:15], v[22:23]
	v_pk_fma_f32 v[32:33], v[16:17], v[24:25], v[32:33]
	v_mul_f32_e32 v34, 0xbfb8aa3b, v40
	v_add_f32_e32 v32, v32, v33
	v_exp_f32_e32 v34, v34
	s_nop 1
	v_add_f32_dpp v32, v32, v32 quad_perm:[1,0,3,2] row_mask:0xf bank_mask:0xf bound_ctrl:1
	s_nop 1
	v_add_f32_dpp v32, v32, v32 quad_perm:[2,3,0,1] row_mask:0xf bank_mask:0xf bound_ctrl:1
	s_nop 1
	v_add_f32_dpp v32, v32, v32 row_half_mirror row_mask:0xf bank_mask:0xf bound_ctrl:1
	s_nop 1
	v_add_f32_dpp v32, v32, v32 row_mirror row_mask:0xf bank_mask:0xf bound_ctrl:1
	v_max_f32_e64 v32, |v32|, v34
	v_rcp_f32_e32 v32, v32
	s_add_i32 s25, s25, 16
	global_store_dword v1, v32, s[22:23] offset:520
	s_branch .Lml_back4
.Lml_den5:
	v_pk_mul_f32 v[32:33], v[14:15], v[22:23]
	v_pk_fma_f32 v[32:33], v[16:17], v[24:25], v[32:33]
	v_mul_f32_e32 v34, 0xbfb8aa3b, v41
	v_add_f32_e32 v32, v32, v33
	v_exp_f32_e32 v34, v34
	s_nop 1
	v_add_f32_dpp v32, v32, v32 quad_perm:[1,0,3,2] row_mask:0xf bank_mask:0xf bound_ctrl:1
	s_nop 1
	v_add_f32_dpp v32, v32, v32 quad_perm:[2,3,0,1] row_mask:0xf bank_mask:0xf bound_ctrl:1
	s_nop 1
	v_add_f32_dpp v32, v32, v32 row_half_mirror row_mask:0xf bank_mask:0xf bound_ctrl:1
	s_nop 1
	v_add_f32_dpp v32, v32, v32 row_mirror row_mask:0xf bank_mask:0xf bound_ctrl:1
	v_max_f32_e64 v32, |v32|, v34
	v_rcp_f32_e32 v32, v32
	s_add_i32 s25, s25, 16
	global_store_dword v1, v32, s[22:23] offset:648
	s_branch .Lml_back5
.Lml_den6:
	v_pk_mul_f32 v[32:33], v[14:15], v[22:23]
	v_pk_fma_f32 v[32:33], v[16:17], v[24:25], v[32:33]
	v_mul_f32_e32 v34, 0xbfb8aa3b, v40
	v_add_f32_e32 v32, v32, v33
	v_exp_f32_e32 v34, v34
	s_nop 1
	v_add_f32_dpp v32, v32, v32 quad_perm:[1,0,3,2] row_mask:0xf bank_mask:0xf bound_ctrl:1
	s_nop 1
	v_add_f32_dpp v32, v32, v32 quad_perm:[2,3,0,1] row_mask:0xf bank_mask:0xf bound_ctrl:1
	s_nop 1
	v_add_f32_dpp v32, v32, v32 row_half_mirror row_mask:0xf bank_mask:0xf bound_ctrl:1
	s_nop 1
	v_add_f32_dpp v32, v32, v32 row_mirror row_mask:0xf bank_mask:0xf bound_ctrl:1
	v_max_f32_e64 v32, |v32|, v34
	v_rcp_f32_e32 v32, v32
	s_add_i32 s25, s25, 16
	global_store_dword v1, v32, s[22:23] offset:776
	s_branch .Lml_back6
.Lml_den7:
	v_pk_mul_f32 v[32:33], v[14:15], v[22:23]
	v_pk_fma_f32 v[32:33], v[16:17], v[24:25], v[32:33]
	v_mul_f32_e32 v34, 0xbfb8aa3b, v41
	v_add_f32_e32 v32, v32, v33
	v_exp_f32_e32 v34, v34
	s_nop 1
	v_add_f32_dpp v32, v32, v32 quad_perm:[1,0,3,2] row_mask:0xf bank_mask:0xf bound_ctrl:1
	s_nop 1
	v_add_f32_dpp v32, v32, v32 quad_perm:[2,3,0,1] row_mask:0xf bank_mask:0xf bound_ctrl:1
	s_nop 1
	v_add_f32_dpp v32, v32, v32 row_half_mirror row_mask:0xf bank_mask:0xf bound_ctrl:1
	s_nop 1
	v_add_f32_dpp v32, v32, v32 row_mirror row_mask:0xf bank_mask:0xf bound_ctrl:1
	v_max_f32_e64 v32, |v32|, v34
	v_rcp_f32_e32 v32, v32
	s_add_i32 s25, s25, 16
	global_store_dword v1, v32, s[22:23] offset:904
	s_branch .Lml_back7

.LBB0_186:
	s_andn2_b64 vcc, exec, s[0:1]
	s_cbranch_vccnz .LBB0_232
	s_and_b64 vcc, exec, s[6:7]
	s_cbranch_vccnz .LBB0_232
	v_readlane_b32 s0, v255, 18
	v_readlane_b32 s1, v255, 19
	s_load_dwordx4 s[8:11], s[0:1], 0xe8
	v_and_b32_e32 v0, 15, v198
	v_lshrrev_b32_e32 v5, 4, v198
	v_lshlrev_b32_e32 v2, 4, v0
	v_lshlrev_b32_e32 v4, 12, v0
	s_mov_b32 s19, 0xffff0000
	s_waitcnt lgkmcnt(0)
.Lgdn_item:
	s_lshr_b32 s0, s27, 4
	s_and_b32 s1, s27, 15
	s_lshr_b32 s2, s0, 3
	s_and_b32 s3, s0, 7
	s_lshl_b32 s4, s1, 4
	v_lshl_add_u32 v3, v5, 2, s4
	v_lshl_add_u32 v153, v3, 1, v4
	s_mul_i32 s4, s2, 0xc00000
	s_lshl_b32 s5, s3, 8
	s_add_u32 s4, s4, s5
	s_add_u32 s4, s4, 0xb38d900
	s_add_u32 s12, s8, s4
	s_addc_u32 s13, s9, 0
	s_lshl_b32 s4, s2, 18
	s_lshl_b32 s6, s3, 4
	s_add_u32 s4, s4, s6
	s_add_u32 s4, s4, 0x37b8400
	s_add_u32 s14, s10, s4
	s_addc_u32 s15, s11, 0
	s_lshl_b32 s4, s2, 23
	s_add_u32 s4, s4, s5
	s_add_u32 s4, s4, 0x13dc0400
	s_add_u32 s16, s10, s4
	s_addc_u32 s17, s11, 0
	s_lshl_b32 s4, s0, 16
	s_add_u32 s4, s4, 0x4080000
	s_add_u32 s20, s8, s4
	s_addc_u32 s21, s9, 0
	global_load_dwordx4 v[56:59], v2, s[12:13]
	global_load_dwordx4 v[60:63], v2, s[12:13] offset:-2048
	global_load_dword v67, v3, s[12:13] offset:2048
	global_load_dwordx3 v[64:66], v1, s[14:15] offset:0
	s_add_u32 s12, s12, 0x1800
	s_addc_u32 s13, s13, 0
	global_load_dwordx4 v[68:71], v2, s[12:13]
	global_load_dwordx4 v[72:75], v2, s[12:13] offset:-2048
	global_load_dword v79, v3, s[12:13] offset:2048
	global_load_dwordx3 v[76:78], v1, s[14:15] offset:128
	s_add_u32 s12, s12, 0x1800
	s_addc_u32 s13, s13, 0
	global_load_dwordx4 v[80:83], v2, s[12:13]
	global_load_dwordx4 v[84:87], v2, s[12:13] offset:-2048
	global_load_dword v91, v3, s[12:13] offset:2048
	global_load_dwordx3 v[88:90], v1, s[14:15] offset:256
	s_add_u32 s12, s12, 0x1800
	s_addc_u32 s13, s13, 0
	global_load_dwordx4 v[92:95], v2, s[12:13]
	global_load_dwordx4 v[96:99], v2, s[12:13] offset:-2048
	global_load_dword v103, v3, s[12:13] offset:2048
	global_load_dwordx3 v[100:102], v1, s[14:15] offset:384
	s_add_u32 s12, s12, 0x1800
	s_addc_u32 s13, s13, 0
	global_load_dwordx4 v[104:107], v2, s[12:13]
	global_load_dwordx4 v[108:111], v2, s[12:13] offset:-2048
	global_load_dword v115, v3, s[12:13] offset:2048
	global_load_dwordx3 v[112:114], v1, s[14:15] offset:512
	s_add_u32 s12, s12, 0x1800
	s_addc_u32 s13, s13, 0
	global_load_dwordx4 v[116:119], v2, s[12:13]
	global_load_dwordx4 v[120:123], v2, s[12:13] offset:-2048
	global_load_dword v127, v3, s[12:13] offset:2048
	global_load_dwordx3 v[124:126], v1, s[14:15] offset:640
	s_add_u32 s12, s12, 0x1800
	s_addc_u32 s13, s13, 0
	global_load_dwordx4 v[128:131], v2, s[12:13]
	global_load_dwordx4 v[132:135], v2, s[12:13] offset:-2048
	global_load_dword v139, v3, s[12:13] offset:2048
	global_load_dwordx3 v[136:138], v1, s[14:15] offset:768
	s_add_u32 s12, s12, 0x1800
	s_addc_u32 s13, s13, 0
	global_load_dwordx4 v[140:143], v2, s[12:13]
	global_load_dwordx4 v[144:147], v2, s[12:13] offset:-2048
	global_load_dword v152, v3, s[12:13] offset:2048
	global_load_dwordx3 v[148:150], v1, s[14:15] offset:896
	s_add_u32 s12, s12, 0x1800
	s_addc_u32 s13, s13, 0
	s_add_u32 s14, s14, 0x400
	s_addc_u32 s15, s15, 0
	v_mov_b32_e32 v6, 0
	v_mov_b32_e32 v7, 0
	v_mov_b32_e32 v8, 0
	v_mov_b32_e32 v9, 0
	v_mov_b32_e32 v10, 0
	v_mov_b32_e32 v11, 0
	v_mov_b32_e32 v12, 0
	v_mov_b32_e32 v13, 0
	v_mov_b32_e32 v14, 0
	v_mov_b32_e32 v15, 0
	v_mov_b32_e32 v16, 0
	v_mov_b32_e32 v17, 0
	v_mov_b32_e32 v18, 0
	v_mov_b32_e32 v19, 0
	v_mov_b32_e32 v20, 0
	v_mov_b32_e32 v21, 0
	v_mov_b32_e32 v51, 1.0
	s_mov_b32 s18, 0
	s_waitcnt vmcnt(0)
.Lgdn_loop:
	s_waitcnt vmcnt(35)
	v_lshlrev_b32_e32 v22, 16, v56
	v_and_b32_e32 v24, s19, v56
	v_lshlrev_b32_e32 v26, 16, v57
	v_and_b32_e32 v28, s19, v57
	v_lshlrev_b32_e32 v30, 16, v58
	v_and_b32_e32 v32, s19, v58
	v_lshlrev_b32_e32 v34, 16, v59
	v_and_b32_e32 v36, s19, v59
	v_lshlrev_b32_e32 v23, 16, v60
	v_and_b32_e32 v25, s19, v60
	v_lshlrev_b32_e32 v27, 16, v61
	v_and_b32_e32 v29, s19, v61
	v_lshlrev_b32_e32 v31, 16, v62
	v_and_b32_e32 v33, s19, v62
	v_lshlrev_b32_e32 v35, 16, v63
	v_and_b32_e32 v37, s19, v63
	v_lshlrev_b32_e32 v42, 16, v67
	v_and_b32_e32 v43, s19, v67
	v_pk_mul_f32 v[38:39], v[6:7], v[22:23] op_sel_hi:[1,0]
	v_pk_mul_f32 v[40:41], v[6:7], v[22:23] op_sel:[0,1] op_sel_hi:[1,1]
	v_pk_fma_f32 v[38:39], v[8:9], v[24:25], v[38:39] op_sel_hi:[1,0,1]
	v_pk_fma_f32 v[40:41], v[8:9], v[24:25], v[40:41] op_sel:[0,1,0] op_sel_hi:[1,1,1]
	v_pk_fma_f32 v[38:39], v[10:11], v[26:27], v[38:39] op_sel_hi:[1,0,1]
	v_pk_fma_f32 v[40:41], v[10:11], v[26:27], v[40:41] op_sel:[0,1,0] op_sel_hi:[1,1,1]
	v_pk_fma_f32 v[38:39], v[12:13], v[28:29], v[38:39] op_sel_hi:[1,0,1]
	v_pk_fma_f32 v[40:41], v[12:13], v[28:29], v[40:41] op_sel:[0,1,0] op_sel_hi:[1,1,1]
	v_pk_fma_f32 v[38:39], v[14:15], v[30:31], v[38:39] op_sel_hi:[1,0,1]
	v_pk_fma_f32 v[40:41], v[14:15], v[30:31], v[40:41] op_sel:[0,1,0] op_sel_hi:[1,1,1]
	v_pk_fma_f32 v[38:39], v[16:17], v[32:33], v[38:39] op_sel_hi:[1,0,1]
	v_pk_fma_f32 v[40:41], v[16:17], v[32:33], v[40:41] op_sel:[0,1,0] op_sel_hi:[1,1,1]
	v_pk_fma_f32 v[38:39], v[18:19], v[34:35], v[38:39] op_sel_hi:[1,0,1]
	v_pk_fma_f32 v[40:41], v[18:19], v[34:35], v[40:41] op_sel:[0,1,0] op_sel_hi:[1,1,1]
	v_pk_fma_f32 v[38:39], v[20:21], v[36:37], v[38:39] op_sel_hi:[1,0,1]
	v_pk_fma_f32 v[40:41], v[20:21], v[36:37], v[40:41] op_sel:[0,1,0] op_sel_hi:[1,1,1]
	v_mul_f32_e32 v50, v64, v51
	v_add_f32_dpp v38, v38, v38 quad_perm:[1,0,3,2] row_mask:0xf bank_mask:0xf bound_ctrl:1
	v_add_f32_dpp v39, v39, v39 quad_perm:[1,0,3,2] row_mask:0xf bank_mask:0xf bound_ctrl:1
	v_add_f32_dpp v40, v40, v40 quad_perm:[1,0,3,2] row_mask:0xf bank_mask:0xf bound_ctrl:1
	v_add_f32_dpp v41, v41, v41 quad_perm:[1,0,3,2] row_mask:0xf bank_mask:0xf bound_ctrl:1
	v_add_f32_dpp v38, v38, v38 quad_perm:[2,3,0,1] row_mask:0xf bank_mask:0xf bound_ctrl:1
	v_add_f32_dpp v39, v39, v39 quad_perm:[2,3,0,1] row_mask:0xf bank_mask:0xf bound_ctrl:1
	v_add_f32_dpp v40, v40, v40 quad_perm:[2,3,0,1] row_mask:0xf bank_mask:0xf bound_ctrl:1
	v_add_f32_dpp v41, v41, v41 quad_perm:[2,3,0,1] row_mask:0xf bank_mask:0xf bound_ctrl:1
	v_add_f32_dpp v38, v38, v38 row_half_mirror row_mask:0xf bank_mask:0xf bound_ctrl:1
	v_add_f32_dpp v39, v39, v39 row_half_mirror row_mask:0xf bank_mask:0xf bound_ctrl:1
	v_add_f32_dpp v40, v40, v40 row_half_mirror row_mask:0xf bank_mask:0xf bound_ctrl:1
	v_add_f32_dpp v41, v41, v41 row_half_mirror row_mask:0xf bank_mask:0xf bound_ctrl:1
	v_add_f32_dpp v38, v38, v38 row_mirror row_mask:0xf bank_mask:0xf bound_ctrl:1
	v_add_f32_dpp v39, v39, v39 row_mirror row_mask:0xf bank_mask:0xf bound_ctrl:1
	v_add_f32_dpp v40, v40, v40 row_mirror row_mask:0xf bank_mask:0xf bound_ctrl:1
	v_add_f32_dpp v41, v41, v41 row_mirror row_mask:0xf bank_mask:0xf bound_ctrl:1
	v_cmp_gt_f32_e32 vcc, 0x2b8cbccc, v50
	v_pk_fma_f32 v[44:45], v[38:39], v[50:51], v[42:43] op_sel:[0,0,0] op_sel_hi:[1,0,1] neg_lo:[1,0,0] neg_hi:[1,0,0]
	v_pk_mul_f32 v[44:45], v[44:45], v[64:65] op_sel:[0,1] op_sel_hi:[1,1]
	v_pk_mul_f32 v[48:49], v[44:45], v[66:67] op_sel_hi:[1,0]
	v_pk_fma_f32 v[48:49], v[40:41], v[50:51], v[48:49] op_sel:[0,0,0] op_sel_hi:[1,0,1]
	s_cbranch_vccnz .Lgdn_rare0
.Lgdn_back0:
	v_rcp_f32_e32 v52, v50
	v_cvt_pk_bf16_f32 v54, v48, v49
	v_pk_mul_f32 v[46:47], v[44:45], v[52:53] op_sel_hi:[1,0]
	v_pk_fma_f32 v[6:7], v[22:23], v[46:47], v[6:7] op_sel_hi:[0,1,1]
	v_pk_fma_f32 v[8:9], v[24:25], v[46:47], v[8:9] op_sel_hi:[0,1,1]
	v_pk_fma_f32 v[10:11], v[26:27], v[46:47], v[10:11] op_sel_hi:[0,1,1]
	v_pk_fma_f32 v[12:13], v[28:29], v[46:47], v[12:13] op_sel_hi:[0,1,1]
	v_pk_fma_f32 v[14:15], v[30:31], v[46:47], v[14:15] op_sel_hi:[0,1,1]
	v_pk_fma_f32 v[16:17], v[32:33], v[46:47], v[16:17] op_sel_hi:[0,1,1]
	v_pk_fma_f32 v[18:19], v[34:35], v[46:47], v[18:19] op_sel_hi:[0,1,1]
	v_pk_fma_f32 v[20:21], v[36:37], v[46:47], v[20:21] op_sel_hi:[0,1,1]
	global_store_dword v3, v54, s[16:17]
	s_add_u32 s16, s16, 0x1000
	s_addc_u32 s17, s17, 0
	global_load_dwordx4 v[56:59], v2, s[12:13]
	global_load_dwordx4 v[60:63], v2, s[12:13] offset:-2048
	global_load_dword v67, v3, s[12:13] offset:2048
	global_load_dwordx3 v[64:66], v1, s[14:15] offset:0
	s_add_u32 s12, s12, 0x1800
	s_addc_u32 s13, s13, 0
	s_waitcnt vmcnt(35)
	v_lshlrev_b32_e32 v22, 16, v68
	v_and_b32_e32 v24, s19, v68
	v_lshlrev_b32_e32 v26, 16, v69
	v_and_b32_e32 v28, s19, v69
	v_lshlrev_b32_e32 v30, 16, v70
	v_and_b32_e32 v32, s19, v70
	v_lshlrev_b32_e32 v34, 16, v71
	v_and_b32_e32 v36, s19, v71
	v_lshlrev_b32_e32 v23, 16, v72
	v_and_b32_e32 v25, s19, v72
	v_lshlrev_b32_e32 v27, 16, v73
	v_and_b32_e32 v29, s19, v73
	v_lshlrev_b32_e32 v31, 16, v74
	v_and_b32_e32 v33, s19, v74
	v_lshlrev_b32_e32 v35, 16, v75
	v_and_b32_e32 v37, s19, v75
	v_lshlrev_b32_e32 v42, 16, v79
	v_and_b32_e32 v43, s19, v79
	v_pk_mul_f32 v[38:39], v[6:7], v[22:23] op_sel_hi:[1,0]
	v_pk_mul_f32 v[40:41], v[6:7], v[22:23] op_sel:[0,1] op_sel_hi:[1,1]
	v_pk_fma_f32 v[38:39], v[8:9], v[24:25], v[38:39] op_sel_hi:[1,0,1]
	v_pk_fma_f32 v[40:41], v[8:9], v[24:25], v[40:41] op_sel:[0,1,0] op_sel_hi:[1,1,1]
	v_pk_fma_f32 v[38:39], v[10:11], v[26:27], v[38:39] op_sel_hi:[1,0,1]
	v_pk_fma_f32 v[40:41], v[10:11], v[26:27], v[40:41] op_sel:[0,1,0] op_sel_hi:[1,1,1]
	v_pk_fma_f32 v[38:39], v[12:13], v[28:29], v[38:39] op_sel_hi:[1,0,1]
	v_pk_fma_f32 v[40:41], v[12:13], v[28:29], v[40:41] op_sel:[0,1,0] op_sel_hi:[1,1,1]
	v_pk_fma_f32 v[38:39], v[14:15], v[30:31], v[38:39] op_sel_hi:[1,0,1]
	v_pk_fma_f32 v[40:41], v[14:15], v[30:31], v[40:41] op_sel:[0,1,0] op_sel_hi:[1,1,1]
	v_pk_fma_f32 v[38:39], v[16:17], v[32:33], v[38:39] op_sel_hi:[1,0,1]
	v_pk_fma_f32 v[40:41], v[16:17], v[32:33], v[40:41] op_sel:[0,1,0] op_sel_hi:[1,1,1]
	v_pk_fma_f32 v[38:39], v[18:19], v[34:35], v[38:39] op_sel_hi:[1,0,1]
	v_pk_fma_f32 v[40:41], v[18:19], v[34:35], v[40:41] op_sel:[0,1,0] op_sel_hi:[1,1,1]
	v_pk_fma_f32 v[38:39], v[20:21], v[36:37], v[38:39] op_sel_hi:[1,0,1]
	v_pk_fma_f32 v[40:41], v[20:21], v[36:37], v[40:41] op_sel:[0,1,0] op_sel_hi:[1,1,1]
	v_mul_f32_e32 v51, v76, v50
	v_add_f32_dpp v38, v38, v38 quad_perm:[1,0,3,2] row_mask:0xf bank_mask:0xf bound_ctrl:1
	v_add_f32_dpp v39, v39, v39 quad_perm:[1,0,3,2] row_mask:0xf bank_mask:0xf bound_ctrl:1
	v_add_f32_dpp v40, v40, v40 quad_perm:[1,0,3,2] row_mask:0xf bank_mask:0xf bound_ctrl:1
	v_add_f32_dpp v41, v41, v41 quad_perm:[1,0,3,2] row_mask:0xf bank_mask:0xf bound_ctrl:1
	v_add_f32_dpp v38, v38, v38 quad_perm:[2,3,0,1] row_mask:0xf bank_mask:0xf bound_ctrl:1
	v_add_f32_dpp v39, v39, v39 quad_perm:[2,3,0,1] row_mask:0xf bank_mask:0xf bound_ctrl:1
	v_add_f32_dpp v40, v40, v40 quad_perm:[2,3,0,1] row_mask:0xf bank_mask:0xf bound_ctrl:1
	v_add_f32_dpp v41, v41, v41 quad_perm:[2,3,0,1] row_mask:0xf bank_mask:0xf bound_ctrl:1
	v_add_f32_dpp v38, v38, v38 row_half_mirror row_mask:0xf bank_mask:0xf bound_ctrl:1
	v_add_f32_dpp v39, v39, v39 row_half_mirror row_mask:0xf bank_mask:0xf bound_ctrl:1
	v_add_f32_dpp v40, v40, v40 row_half_mirror row_mask:0xf bank_mask:0xf bound_ctrl:1
	v_add_f32_dpp v41, v41, v41 row_half_mirror row_mask:0xf bank_mask:0xf bound_ctrl:1
	v_add_f32_dpp v38, v38, v38 row_mirror row_mask:0xf bank_mask:0xf bound_ctrl:1
	v_add_f32_dpp v39, v39, v39 row_mirror row_mask:0xf bank_mask:0xf bound_ctrl:1
	v_add_f32_dpp v40, v40, v40 row_mirror row_mask:0xf bank_mask:0xf bound_ctrl:1
	v_add_f32_dpp v41, v41, v41 row_mirror row_mask:0xf bank_mask:0xf bound_ctrl:1
	v_cmp_gt_f32_e32 vcc, 0x2b8cbccc, v51
	v_pk_fma_f32 v[44:45], v[38:39], v[50:51], v[42:43] op_sel:[0,1,0] op_sel_hi:[1,1,1] neg_lo:[1,0,0] neg_hi:[1,0,0]
	v_pk_mul_f32 v[44:45], v[44:45], v[76:77] op_sel:[0,1] op_sel_hi:[1,1]
	v_pk_mul_f32 v[48:49], v[44:45], v[78:79] op_sel_hi:[1,0]
	v_pk_fma_f32 v[48:49], v[40:41], v[50:51], v[48:49] op_sel:[0,1,0] op_sel_hi:[1,1,1]
	s_cbranch_vccnz .Lgdn_rare1
.Lgdn_back1:
	v_rcp_f32_e32 v52, v51
	v_cvt_pk_bf16_f32 v54, v48, v49
	v_pk_mul_f32 v[46:47], v[44:45], v[52:53] op_sel_hi:[1,0]
	v_pk_fma_f32 v[6:7], v[22:23], v[46:47], v[6:7] op_sel_hi:[0,1,1]
	v_pk_fma_f32 v[8:9], v[24:25], v[46:47], v[8:9] op_sel_hi:[0,1,1]
	v_pk_fma_f32 v[10:11], v[26:27], v[46:47], v[10:11] op_sel_hi:[0,1,1]
	v_pk_fma_f32 v[12:13], v[28:29], v[46:47], v[12:13] op_sel_hi:[0,1,1]
	v_pk_fma_f32 v[14:15], v[30:31], v[46:47], v[14:15] op_sel_hi:[0,1,1]
	v_pk_fma_f32 v[16:17], v[32:33], v[46:47], v[16:17] op_sel_hi:[0,1,1]
	v_pk_fma_f32 v[18:19], v[34:35], v[46:47], v[18:19] op_sel_hi:[0,1,1]
	v_pk_fma_f32 v[20:21], v[36:37], v[46:47], v[20:21] op_sel_hi:[0,1,1]
	global_store_dword v3, v54, s[16:17]
	s_add_u32 s16, s16, 0x1000
	s_addc_u32 s17, s17, 0
	global_load_dwordx4 v[68:71], v2, s[12:13]
	global_load_dwordx4 v[72:75], v2, s[12:13] offset:-2048
	global_load_dword v79, v3, s[12:13] offset:2048
	global_load_dwordx3 v[76:78], v1, s[14:15] offset:128
	s_add_u32 s12, s12, 0x1800
	s_addc_u32 s13, s13, 0
	s_waitcnt vmcnt(35)
	v_lshlrev_b32_e32 v22, 16, v80
	v_and_b32_e32 v24, s19, v80
	v_lshlrev_b32_e32 v26, 16, v81
	v_and_b32_e32 v28, s19, v81
	v_lshlrev_b32_e32 v30, 16, v82
	v_and_b32_e32 v32, s19, v82
	v_lshlrev_b32_e32 v34, 16, v83
	v_and_b32_e32 v36, s19, v83
	v_lshlrev_b32_e32 v23, 16, v84
	v_and_b32_e32 v25, s19, v84
	v_lshlrev_b32_e32 v27, 16, v85
	v_and_b32_e32 v29, s19, v85
	v_lshlrev_b32_e32 v31, 16, v86
	v_and_b32_e32 v33, s19, v86
	v_lshlrev_b32_e32 v35, 16, v87
	v_and_b32_e32 v37, s19, v87
	v_lshlrev_b32_e32 v42, 16, v91
	v_and_b32_e32 v43, s19, v91
	v_pk_mul_f32 v[38:39], v[6:7], v[22:23] op_sel_hi:[1,0]
	v_pk_mul_f32 v[40:41], v[6:7], v[22:23] op_sel:[0,1] op_sel_hi:[1,1]
	v_pk_fma_f32 v[38:39], v[8:9], v[24:25], v[38:39] op_sel_hi:[1,0,1]
	v_pk_fma_f32 v[40:41], v[8:9], v[24:25], v[40:41] op_sel:[0,1,0] op_sel_hi:[1,1,1]
	v_pk_fma_f32 v[38:39], v[10:11], v[26:27], v[38:39] op_sel_hi:[1,0,1]
	v_pk_fma_f32 v[40:41], v[10:11], v[26:27], v[40:41] op_sel:[0,1,0] op_sel_hi:[1,1,1]
	v_pk_fma_f32 v[38:39], v[12:13], v[28:29], v[38:39] op_sel_hi:[1,0,1]
	v_pk_fma_f32 v[40:41], v[12:13], v[28:29], v[40:41] op_sel:[0,1,0] op_sel_hi:[1,1,1]
	v_pk_fma_f32 v[38:39], v[14:15], v[30:31], v[38:39] op_sel_hi:[1,0,1]
	v_pk_fma_f32 v[40:41], v[14:15], v[30:31], v[40:41] op_sel:[0,1,0] op_sel_hi:[1,1,1]
	v_pk_fma_f32 v[38:39], v[16:17], v[32:33], v[38:39] op_sel_hi:[1,0,1]
	v_pk_fma_f32 v[40:41], v[16:17], v[32:33], v[40:41] op_sel:[0,1,0] op_sel_hi:[1,1,1]
	v_pk_fma_f32 v[38:39], v[18:19], v[34:35], v[38:39] op_sel_hi:[1,0,1]
	v_pk_fma_f32 v[40:41], v[18:19], v[34:35], v[40:41] op_sel:[0,1,0] op_sel_hi:[1,1,1]
	v_pk_fma_f32 v[38:39], v[20:21], v[36:37], v[38:39] op_sel_hi:[1,0,1]
	v_pk_fma_f32 v[40:41], v[20:21], v[36:37], v[40:41] op_sel:[0,1,0] op_sel_hi:[1,1,1]
	v_mul_f32_e32 v50, v88, v51
	v_add_f32_dpp v38, v38, v38 quad_perm:[1,0,3,2] row_mask:0xf bank_mask:0xf bound_ctrl:1
	v_add_f32_dpp v39, v39, v39 quad_perm:[1,0,3,2] row_mask:0xf bank_mask:0xf bound_ctrl:1
	v_add_f32_dpp v40, v40, v40 quad_perm:[1,0,3,2] row_mask:0xf bank_mask:0xf bound_ctrl:1
	v_add_f32_dpp v41, v41, v41 quad_perm:[1,0,3,2] row_mask:0xf bank_mask:0xf bound_ctrl:1
	v_add_f32_dpp v38, v38, v38 quad_perm:[2,3,0,1] row_mask:0xf bank_mask:0xf bound_ctrl:1
	v_add_f32_dpp v39, v39, v39 quad_perm:[2,3,0,1] row_mask:0xf bank_mask:0xf bound_ctrl:1
	v_add_f32_dpp v40, v40, v40 quad_perm:[2,3,0,1] row_mask:0xf bank_mask:0xf bound_ctrl:1
	v_add_f32_dpp v41, v41, v41 quad_perm:[2,3,0,1] row_mask:0xf bank_mask:0xf bound_ctrl:1
	v_add_f32_dpp v38, v38, v38 row_half_mirror row_mask:0xf bank_mask:0xf bound_ctrl:1
	v_add_f32_dpp v39, v39, v39 row_half_mirror row_mask:0xf bank_mask:0xf bound_ctrl:1
	v_add_f32_dpp v40, v40, v40 row_half_mirror row_mask:0xf bank_mask:0xf bound_ctrl:1
	v_add_f32_dpp v41, v41, v41 row_half_mirror row_mask:0xf bank_mask:0xf bound_ctrl:1
	v_add_f32_dpp v38, v38, v38 row_mirror row_mask:0xf bank_mask:0xf bound_ctrl:1
	v_add_f32_dpp v39, v39, v39 row_mirror row_mask:0xf bank_mask:0xf bound_ctrl:1
	v_add_f32_dpp v40, v40, v40 row_mirror row_mask:0xf bank_mask:0xf bound_ctrl:1
	v_add_f32_dpp v41, v41, v41 row_mirror row_mask:0xf bank_mask:0xf bound_ctrl:1
	v_cmp_gt_f32_e32 vcc, 0x2b8cbccc, v50
	v_pk_fma_f32 v[44:45], v[38:39], v[50:51], v[42:43] op_sel:[0,0,0] op_sel_hi:[1,0,1] neg_lo:[1,0,0] neg_hi:[1,0,0]
	v_pk_mul_f32 v[44:45], v[44:45], v[88:89] op_sel:[0,1] op_sel_hi:[1,1]
	v_pk_mul_f32 v[48:49], v[44:45], v[90:91] op_sel_hi:[1,0]
	v_pk_fma_f32 v[48:49], v[40:41], v[50:51], v[48:49] op_sel:[0,0,0] op_sel_hi:[1,0,1]
	s_cbranch_vccnz .Lgdn_rare2
.Lgdn_back2:
	v_rcp_f32_e32 v52, v50
	v_cvt_pk_bf16_f32 v54, v48, v49
	v_pk_mul_f32 v[46:47], v[44:45], v[52:53] op_sel_hi:[1,0]
	v_pk_fma_f32 v[6:7], v[22:23], v[46:47], v[6:7] op_sel_hi:[0,1,1]
	v_pk_fma_f32 v[8:9], v[24:25], v[46:47], v[8:9] op_sel_hi:[0,1,1]
	v_pk_fma_f32 v[10:11], v[26:27], v[46:47], v[10:11] op_sel_hi:[0,1,1]
	v_pk_fma_f32 v[12:13], v[28:29], v[46:47], v[12:13] op_sel_hi:[0,1,1]
	v_pk_fma_f32 v[14:15], v[30:31], v[46:47], v[14:15] op_sel_hi:[0,1,1]
	v_pk_fma_f32 v[16:17], v[32:33], v[46:47], v[16:17] op_sel_hi:[0,1,1]
	v_pk_fma_f32 v[18:19], v[34:35], v[46:47], v[18:19] op_sel_hi:[0,1,1]
	v_pk_fma_f32 v[20:21], v[36:37], v[46:47], v[20:21] op_sel_hi:[0,1,1]
	global_store_dword v3, v54, s[16:17]
	s_add_u32 s16, s16, 0x1000
	s_addc_u32 s17, s17, 0
	global_load_dwordx4 v[80:83], v2, s[12:13]
	global_load_dwordx4 v[84:87], v2, s[12:13] offset:-2048
	global_load_dword v91, v3, s[12:13] offset:2048
	global_load_dwordx3 v[88:90], v1, s[14:15] offset:256
	s_add_u32 s12, s12, 0x1800
	s_addc_u32 s13, s13, 0
	s_waitcnt vmcnt(35)
	v_lshlrev_b32_e32 v22, 16, v92
	v_and_b32_e32 v24, s19, v92
	v_lshlrev_b32_e32 v26, 16, v93
	v_and_b32_e32 v28, s19, v93
	v_lshlrev_b32_e32 v30, 16, v94
	v_and_b32_e32 v32, s19, v94
	v_lshlrev_b32_e32 v34, 16, v95
	v_and_b32_e32 v36, s19, v95
	v_lshlrev_b32_e32 v23, 16, v96
	v_and_b32_e32 v25, s19, v96
	v_lshlrev_b32_e32 v27, 16, v97
	v_and_b32_e32 v29, s19, v97
	v_lshlrev_b32_e32 v31, 16, v98
	v_and_b32_e32 v33, s19, v98
	v_lshlrev_b32_e32 v35, 16, v99
	v_and_b32_e32 v37, s19, v99
	v_lshlrev_b32_e32 v42, 16, v103
	v_and_b32_e32 v43, s19, v103
	v_pk_mul_f32 v[38:39], v[6:7], v[22:23] op_sel_hi:[1,0]
	v_pk_mul_f32 v[40:41], v[6:7], v[22:23] op_sel:[0,1] op_sel_hi:[1,1]
	v_pk_fma_f32 v[38:39], v[8:9], v[24:25], v[38:39] op_sel_hi:[1,0,1]
	v_pk_fma_f32 v[40:41], v[8:9], v[24:25], v[40:41] op_sel:[0,1,0] op_sel_hi:[1,1,1]
	v_pk_fma_f32 v[38:39], v[10:11], v[26:27], v[38:39] op_sel_hi:[1,0,1]
	v_pk_fma_f32 v[40:41], v[10:11], v[26:27], v[40:41] op_sel:[0,1,0] op_sel_hi:[1,1,1]
	v_pk_fma_f32 v[38:39], v[12:13], v[28:29], v[38:39] op_sel_hi:[1,0,1]
	v_pk_fma_f32 v[40:41], v[12:13], v[28:29], v[40:41] op_sel:[0,1,0] op_sel_hi:[1,1,1]
	v_pk_fma_f32 v[38:39], v[14:15], v[30:31], v[38:39] op_sel_hi:[1,0,1]
	v_pk_fma_f32 v[40:41], v[14:15], v[30:31], v[40:41] op_sel:[0,1,0] op_sel_hi:[1,1,1]
	v_pk_fma_f32 v[38:39], v[16:17], v[32:33], v[38:39] op_sel_hi:[1,0,1]
	v_pk_fma_f32 v[40:41], v[16:17], v[32:33], v[40:41] op_sel:[0,1,0] op_sel_hi:[1,1,1]
	v_pk_fma_f32 v[38:39], v[18:19], v[34:35], v[38:39] op_sel_hi:[1,0,1]
	v_pk_fma_f32 v[40:41], v[18:19], v[34:35], v[40:41] op_sel:[0,1,0] op_sel_hi:[1,1,1]
	v_pk_fma_f32 v[38:39], v[20:21], v[36:37], v[38:39] op_sel_hi:[1,0,1]
	v_pk_fma_f32 v[40:41], v[20:21], v[36:37], v[40:41] op_sel:[0,1,0] op_sel_hi:[1,1,1]
	v_mul_f32_e32 v51, v100, v50
	v_add_f32_dpp v38, v38, v38 quad_perm:[1,0,3,2] row_mask:0xf bank_mask:0xf bound_ctrl:1
	v_add_f32_dpp v39, v39, v39 quad_perm:[1,0,3,2] row_mask:0xf bank_mask:0xf bound_ctrl:1
	v_add_f32_dpp v40, v40, v40 quad_perm:[1,0,3,2] row_mask:0xf bank_mask:0xf bound_ctrl:1
	v_add_f32_dpp v41, v41, v41 quad_perm:[1,0,3,2] row_mask:0xf bank_mask:0xf bound_ctrl:1
	v_add_f32_dpp v38, v38, v38 quad_perm:[2,3,0,1] row_mask:0xf bank_mask:0xf bound_ctrl:1
	v_add_f32_dpp v39, v39, v39 quad_perm:[2,3,0,1] row_mask:0xf bank_mask:0xf bound_ctrl:1
	v_add_f32_dpp v40, v40, v40 quad_perm:[2,3,0,1] row_mask:0xf bank_mask:0xf bound_ctrl:1
	v_add_f32_dpp v41, v41, v41 quad_perm:[2,3,0,1] row_mask:0xf bank_mask:0xf bound_ctrl:1
	v_add_f32_dpp v38, v38, v38 row_half_mirror row_mask:0xf bank_mask:0xf bound_ctrl:1
	v_add_f32_dpp v39, v39, v39 row_half_mirror row_mask:0xf bank_mask:0xf bound_ctrl:1
	v_add_f32_dpp v40, v40, v40 row_half_mirror row_mask:0xf bank_mask:0xf bound_ctrl:1
	v_add_f32_dpp v41, v41, v41 row_half_mirror row_mask:0xf bank_mask:0xf bound_ctrl:1
	v_add_f32_dpp v38, v38, v38 row_mirror row_mask:0xf bank_mask:0xf bound_ctrl:1
	v_add_f32_dpp v39, v39, v39 row_mirror row_mask:0xf bank_mask:0xf bound_ctrl:1
	v_add_f32_dpp v40, v40, v40 row_mirror row_mask:0xf bank_mask:0xf bound_ctrl:1
	v_add_f32_dpp v41, v41, v41 row_mirror row_mask:0xf bank_mask:0xf bound_ctrl:1
	v_cmp_gt_f32_e32 vcc, 0x2b8cbccc, v51
	v_pk_fma_f32 v[44:45], v[38:39], v[50:51], v[42:43] op_sel:[0,1,0] op_sel_hi:[1,1,1] neg_lo:[1,0,0] neg_hi:[1,0,0]
	v_pk_mul_f32 v[44:45], v[44:45], v[100:101] op_sel:[0,1] op_sel_hi:[1,1]
	v_pk_mul_f32 v[48:49], v[44:45], v[102:103] op_sel_hi:[1,0]
	v_pk_fma_f32 v[48:49], v[40:41], v[50:51], v[48:49] op_sel:[0,1,0] op_sel_hi:[1,1,1]
	s_cbranch_vccnz .Lgdn_rare3
.Lgdn_back3:
	v_rcp_f32_e32 v52, v51
	v_cvt_pk_bf16_f32 v54, v48, v49
	v_pk_mul_f32 v[46:47], v[44:45], v[52:53] op_sel_hi:[1,0]
	v_pk_fma_f32 v[6:7], v[22:23], v[46:47], v[6:7] op_sel_hi:[0,1,1]
	v_pk_fma_f32 v[8:9], v[24:25], v[46:47], v[8:9] op_sel_hi:[0,1,1]
	v_pk_fma_f32 v[10:11], v[26:27], v[46:47], v[10:11] op_sel_hi:[0,1,1]
	v_pk_fma_f32 v[12:13], v[28:29], v[46:47], v[12:13] op_sel_hi:[0,1,1]
	v_pk_fma_f32 v[14:15], v[30:31], v[46:47], v[14:15] op_sel_hi:[0,1,1]
	v_pk_fma_f32 v[16:17], v[32:33], v[46:47], v[16:17] op_sel_hi:[0,1,1]
	v_pk_fma_f32 v[18:19], v[34:35], v[46:47], v[18:19] op_sel_hi:[0,1,1]
	v_pk_fma_f32 v[20:21], v[36:37], v[46:47], v[20:21] op_sel_hi:[0,1,1]
	global_store_dword v3, v54, s[16:17]
	s_add_u32 s16, s16, 0x1000
	s_addc_u32 s17, s17, 0
	global_load_dwordx4 v[92:95], v2, s[12:13]
	global_load_dwordx4 v[96:99], v2, s[12:13] offset:-2048
	global_load_dword v103, v3, s[12:13] offset:2048
	global_load_dwordx3 v[100:102], v1, s[14:15] offset:384
	s_add_u32 s12, s12, 0x1800
	s_addc_u32 s13, s13, 0
	s_waitcnt vmcnt(35)
	v_lshlrev_b32_e32 v22, 16, v104
	v_and_b32_e32 v24, s19, v104
	v_lshlrev_b32_e32 v26, 16, v105
	v_and_b32_e32 v28, s19, v105
	v_lshlrev_b32_e32 v30, 16, v106
	v_and_b32_e32 v32, s19, v106
	v_lshlrev_b32_e32 v34, 16, v107
	v_and_b32_e32 v36, s19, v107
	v_lshlrev_b32_e32 v23, 16, v108
	v_and_b32_e32 v25, s19, v108
	v_lshlrev_b32_e32 v27, 16, v109
	v_and_b32_e32 v29, s19, v109
	v_lshlrev_b32_e32 v31, 16, v110
	v_and_b32_e32 v33, s19, v110
	v_lshlrev_b32_e32 v35, 16, v111
	v_and_b32_e32 v37, s19, v111
	v_lshlrev_b32_e32 v42, 16, v115
	v_and_b32_e32 v43, s19, v115
	v_pk_mul_f32 v[38:39], v[6:7], v[22:23] op_sel_hi:[1,0]
	v_pk_mul_f32 v[40:41], v[6:7], v[22:23] op_sel:[0,1] op_sel_hi:[1,1]
	v_pk_fma_f32 v[38:39], v[8:9], v[24:25], v[38:39] op_sel_hi:[1,0,1]
	v_pk_fma_f32 v[40:41], v[8:9], v[24:25], v[40:41] op_sel:[0,1,0] op_sel_hi:[1,1,1]
	v_pk_fma_f32 v[38:39], v[10:11], v[26:27], v[38:39] op_sel_hi:[1,0,1]
	v_pk_fma_f32 v[40:41], v[10:11], v[26:27], v[40:41] op_sel:[0,1,0] op_sel_hi:[1,1,1]
	v_pk_fma_f32 v[38:39], v[12:13], v[28:29], v[38:39] op_sel_hi:[1,0,1]
	v_pk_fma_f32 v[40:41], v[12:13], v[28:29], v[40:41] op_sel:[0,1,0] op_sel_hi:[1,1,1]
	v_pk_fma_f32 v[38:39], v[14:15], v[30:31], v[38:39] op_sel_hi:[1,0,1]
	v_pk_fma_f32 v[40:41], v[14:15], v[30:31], v[40:41] op_sel:[0,1,0] op_sel_hi:[1,1,1]
	v_pk_fma_f32 v[38:39], v[16:17], v[32:33], v[38:39] op_sel_hi:[1,0,1]
	v_pk_fma_f32 v[40:41], v[16:17], v[32:33], v[40:41] op_sel:[0,1,0] op_sel_hi:[1,1,1]
	v_pk_fma_f32 v[38:39], v[18:19], v[34:35], v[38:39] op_sel_hi:[1,0,1]
	v_pk_fma_f32 v[40:41], v[18:19], v[34:35], v[40:41] op_sel:[0,1,0] op_sel_hi:[1,1,1]
	v_pk_fma_f32 v[38:39], v[20:21], v[36:37], v[38:39] op_sel_hi:[1,0,1]
	v_pk_fma_f32 v[40:41], v[20:21], v[36:37], v[40:41] op_sel:[0,1,0] op_sel_hi:[1,1,1]
	v_mul_f32_e32 v50, v112, v51
	v_add_f32_dpp v38, v38, v38 quad_perm:[1,0,3,2] row_mask:0xf bank_mask:0xf bound_ctrl:1
	v_add_f32_dpp v39, v39, v39 quad_perm:[1,0,3,2] row_mask:0xf bank_mask:0xf bound_ctrl:1
	v_add_f32_dpp v40, v40, v40 quad_perm:[1,0,3,2] row_mask:0xf bank_mask:0xf bound_ctrl:1
	v_add_f32_dpp v41, v41, v41 quad_perm:[1,0,3,2] row_mask:0xf bank_mask:0xf bound_ctrl:1
	v_add_f32_dpp v38, v38, v38 quad_perm:[2,3,0,1] row_mask:0xf bank_mask:0xf bound_ctrl:1
	v_add_f32_dpp v39, v39, v39 quad_perm:[2,3,0,1] row_mask:0xf bank_mask:0xf bound_ctrl:1
	v_add_f32_dpp v40, v40, v40 quad_perm:[2,3,0,1] row_mask:0xf bank_mask:0xf bound_ctrl:1
	v_add_f32_dpp v41, v41, v41 quad_perm:[2,3,0,1] row_mask:0xf bank_mask:0xf bound_ctrl:1
	v_add_f32_dpp v38, v38, v38 row_half_mirror row_mask:0xf bank_mask:0xf bound_ctrl:1
	v_add_f32_dpp v39, v39, v39 row_half_mirror row_mask:0xf bank_mask:0xf bound_ctrl:1
	v_add_f32_dpp v40, v40, v40 row_half_mirror row_mask:0xf bank_mask:0xf bound_ctrl:1
	v_add_f32_dpp v41, v41, v41 row_half_mirror row_mask:0xf bank_mask:0xf bound_ctrl:1
	v_add_f32_dpp v38, v38, v38 row_mirror row_mask:0xf bank_mask:0xf bound_ctrl:1
	v_add_f32_dpp v39, v39, v39 row_mirror row_mask:0xf bank_mask:0xf bound_ctrl:1
	v_add_f32_dpp v40, v40, v40 row_mirror row_mask:0xf bank_mask:0xf bound_ctrl:1
	v_add_f32_dpp v41, v41, v41 row_mirror row_mask:0xf bank_mask:0xf bound_ctrl:1
	v_cmp_gt_f32_e32 vcc, 0x2b8cbccc, v50
	v_pk_fma_f32 v[44:45], v[38:39], v[50:51], v[42:43] op_sel:[0,0,0] op_sel_hi:[1,0,1] neg_lo:[1,0,0] neg_hi:[1,0,0]
	v_pk_mul_f32 v[44:45], v[44:45], v[112:113] op_sel:[0,1] op_sel_hi:[1,1]
	v_pk_mul_f32 v[48:49], v[44:45], v[114:115] op_sel_hi:[1,0]
	v_pk_fma_f32 v[48:49], v[40:41], v[50:51], v[48:49] op_sel:[0,0,0] op_sel_hi:[1,0,1]
	s_cbranch_vccnz .Lgdn_rare4
.Lgdn_back4:
	v_rcp_f32_e32 v52, v50
	v_cvt_pk_bf16_f32 v54, v48, v49
	v_pk_mul_f32 v[46:47], v[44:45], v[52:53] op_sel_hi:[1,0]
	v_pk_fma_f32 v[6:7], v[22:23], v[46:47], v[6:7] op_sel_hi:[0,1,1]
	v_pk_fma_f32 v[8:9], v[24:25], v[46:47], v[8:9] op_sel_hi:[0,1,1]
	v_pk_fma_f32 v[10:11], v[26:27], v[46:47], v[10:11] op_sel_hi:[0,1,1]
	v_pk_fma_f32 v[12:13], v[28:29], v[46:47], v[12:13] op_sel_hi:[0,1,1]
	v_pk_fma_f32 v[14:15], v[30:31], v[46:47], v[14:15] op_sel_hi:[0,1,1]
	v_pk_fma_f32 v[16:17], v[32:33], v[46:47], v[16:17] op_sel_hi:[0,1,1]
	v_pk_fma_f32 v[18:19], v[34:35], v[46:47], v[18:19] op_sel_hi:[0,1,1]
	v_pk_fma_f32 v[20:21], v[36:37], v[46:47], v[20:21] op_sel_hi:[0,1,1]
	global_store_dword v3, v54, s[16:17]
	s_add_u32 s16, s16, 0x1000
	s_addc_u32 s17, s17, 0
	global_load_dwordx4 v[104:107], v2, s[12:13]
	global_load_dwordx4 v[108:111], v2, s[12:13] offset:-2048
	global_load_dword v115, v3, s[12:13] offset:2048
	global_load_dwordx3 v[112:114], v1, s[14:15] offset:512
	s_add_u32 s12, s12, 0x1800
	s_addc_u32 s13, s13, 0
	s_waitcnt vmcnt(35)
	v_lshlrev_b32_e32 v22, 16, v116
	v_and_b32_e32 v24, s19, v116
	v_lshlrev_b32_e32 v26, 16, v117
	v_and_b32_e32 v28, s19, v117
	v_lshlrev_b32_e32 v30, 16, v118
	v_and_b32_e32 v32, s19, v118
	v_lshlrev_b32_e32 v34, 16, v119
	v_and_b32_e32 v36, s19, v119
	v_lshlrev_b32_e32 v23, 16, v120
	v_and_b32_e32 v25, s19, v120
	v_lshlrev_b32_e32 v27, 16, v121
	v_and_b32_e32 v29, s19, v121
	v_lshlrev_b32_e32 v31, 16, v122
	v_and_b32_e32 v33, s19, v122
	v_lshlrev_b32_e32 v35, 16, v123
	v_and_b32_e32 v37, s19, v123
	v_lshlrev_b32_e32 v42, 16, v127
	v_and_b32_e32 v43, s19, v127
	v_pk_mul_f32 v[38:39], v[6:7], v[22:23] op_sel_hi:[1,0]
	v_pk_mul_f32 v[40:41], v[6:7], v[22:23] op_sel:[0,1] op_sel_hi:[1,1]
	v_pk_fma_f32 v[38:39], v[8:9], v[24:25], v[38:39] op_sel_hi:[1,0,1]
	v_pk_fma_f32 v[40:41], v[8:9], v[24:25], v[40:41] op_sel:[0,1,0] op_sel_hi:[1,1,1]
	v_pk_fma_f32 v[38:39], v[10:11], v[26:27], v[38:39] op_sel_hi:[1,0,1]
	v_pk_fma_f32 v[40:41], v[10:11], v[26:27], v[40:41] op_sel:[0,1,0] op_sel_hi:[1,1,1]
	v_pk_fma_f32 v[38:39], v[12:13], v[28:29], v[38:39] op_sel_hi:[1,0,1]
	v_pk_fma_f32 v[40:41], v[12:13], v[28:29], v[40:41] op_sel:[0,1,0] op_sel_hi:[1,1,1]
	v_pk_fma_f32 v[38:39], v[14:15], v[30:31], v[38:39] op_sel_hi:[1,0,1]
	v_pk_fma_f32 v[40:41], v[14:15], v[30:31], v[40:41] op_sel:[0,1,0] op_sel_hi:[1,1,1]
	v_pk_fma_f32 v[38:39], v[16:17], v[32:33], v[38:39] op_sel_hi:[1,0,1]
	v_pk_fma_f32 v[40:41], v[16:17], v[32:33], v[40:41] op_sel:[0,1,0] op_sel_hi:[1,1,1]
	v_pk_fma_f32 v[38:39], v[18:19], v[34:35], v[38:39] op_sel_hi:[1,0,1]
	v_pk_fma_f32 v[40:41], v[18:19], v[34:35], v[40:41] op_sel:[0,1,0] op_sel_hi:[1,1,1]
	v_pk_fma_f32 v[38:39], v[20:21], v[36:37], v[38:39] op_sel_hi:[1,0,1]
	v_pk_fma_f32 v[40:41], v[20:21], v[36:37], v[40:41] op_sel:[0,1,0] op_sel_hi:[1,1,1]
	v_mul_f32_e32 v51, v124, v50
	v_add_f32_dpp v38, v38, v38 quad_perm:[1,0,3,2] row_mask:0xf bank_mask:0xf bound_ctrl:1
	v_add_f32_dpp v39, v39, v39 quad_perm:[1,0,3,2] row_mask:0xf bank_mask:0xf bound_ctrl:1
	v_add_f32_dpp v40, v40, v40 quad_perm:[1,0,3,2] row_mask:0xf bank_mask:0xf bound_ctrl:1
	v_add_f32_dpp v41, v41, v41 quad_perm:[1,0,3,2] row_mask:0xf bank_mask:0xf bound_ctrl:1
	v_add_f32_dpp v38, v38, v38 quad_perm:[2,3,0,1] row_mask:0xf bank_mask:0xf bound_ctrl:1
	v_add_f32_dpp v39, v39, v39 quad_perm:[2,3,0,1] row_mask:0xf bank_mask:0xf bound_ctrl:1
	v_add_f32_dpp v40, v40, v40 quad_perm:[2,3,0,1] row_mask:0xf bank_mask:0xf bound_ctrl:1
	v_add_f32_dpp v41, v41, v41 quad_perm:[2,3,0,1] row_mask:0xf bank_mask:0xf bound_ctrl:1
	v_add_f32_dpp v38, v38, v38 row_half_mirror row_mask:0xf bank_mask:0xf bound_ctrl:1
	v_add_f32_dpp v39, v39, v39 row_half_mirror row_mask:0xf bank_mask:0xf bound_ctrl:1
	v_add_f32_dpp v40, v40, v40 row_half_mirror row_mask:0xf bank_mask:0xf bound_ctrl:1
	v_add_f32_dpp v41, v41, v41 row_half_mirror row_mask:0xf bank_mask:0xf bound_ctrl:1
	v_add_f32_dpp v38, v38, v38 row_mirror row_mask:0xf bank_mask:0xf bound_ctrl:1
	v_add_f32_dpp v39, v39, v39 row_mirror row_mask:0xf bank_mask:0xf bound_ctrl:1
	v_add_f32_dpp v40, v40, v40 row_mirror row_mask:0xf bank_mask:0xf bound_ctrl:1
	v_add_f32_dpp v41, v41, v41 row_mirror row_mask:0xf bank_mask:0xf bound_ctrl:1
	v_cmp_gt_f32_e32 vcc, 0x2b8cbccc, v51
	v_pk_fma_f32 v[44:45], v[38:39], v[50:51], v[42:43] op_sel:[0,1,0] op_sel_hi:[1,1,1] neg_lo:[1,0,0] neg_hi:[1,0,0]
	v_pk_mul_f32 v[44:45], v[44:45], v[124:125] op_sel:[0,1] op_sel_hi:[1,1]
	v_pk_mul_f32 v[48:49], v[44:45], v[126:127] op_sel_hi:[1,0]
	v_pk_fma_f32 v[48:49], v[40:41], v[50:51], v[48:49] op_sel:[0,1,0] op_sel_hi:[1,1,1]
	s_cbranch_vccnz .Lgdn_rare5
.Lgdn_back5:
	v_rcp_f32_e32 v52, v51
	v_cvt_pk_bf16_f32 v54, v48, v49
	v_pk_mul_f32 v[46:47], v[44:45], v[52:53] op_sel_hi:[1,0]
	v_pk_fma_f32 v[6:7], v[22:23], v[46:47], v[6:7] op_sel_hi:[0,1,1]
	v_pk_fma_f32 v[8:9], v[24:25], v[46:47], v[8:9] op_sel_hi:[0,1,1]
	v_pk_fma_f32 v[10:11], v[26:27], v[46:47], v[10:11] op_sel_hi:[0,1,1]
	v_pk_fma_f32 v[12:13], v[28:29], v[46:47], v[12:13] op_sel_hi:[0,1,1]
	v_pk_fma_f32 v[14:15], v[30:31], v[46:47], v[14:15] op_sel_hi:[0,1,1]
	v_pk_fma_f32 v[16:17], v[32:33], v[46:47], v[16:17] op_sel_hi:[0,1,1]
	v_pk_fma_f32 v[18:19], v[34:35], v[46:47], v[18:19] op_sel_hi:[0,1,1]
	v_pk_fma_f32 v[20:21], v[36:37], v[46:47], v[20:21] op_sel_hi:[0,1,1]
	global_store_dword v3, v54, s[16:17]
	s_add_u32 s16, s16, 0x1000
	s_addc_u32 s17, s17, 0
	global_load_dwordx4 v[116:119], v2, s[12:13]
	global_load_dwordx4 v[120:123], v2, s[12:13] offset:-2048
	global_load_dword v127, v3, s[12:13] offset:2048
	global_load_dwordx3 v[124:126], v1, s[14:15] offset:640
	s_add_u32 s12, s12, 0x1800
	s_addc_u32 s13, s13, 0
	s_waitcnt vmcnt(35)
	v_lshlrev_b32_e32 v22, 16, v128
	v_and_b32_e32 v24, s19, v128
	v_lshlrev_b32_e32 v26, 16, v129
	v_and_b32_e32 v28, s19, v129
	v_lshlrev_b32_e32 v30, 16, v130
	v_and_b32_e32 v32, s19, v130
	v_lshlrev_b32_e32 v34, 16, v131
	v_and_b32_e32 v36, s19, v131
	v_lshlrev_b32_e32 v23, 16, v132
	v_and_b32_e32 v25, s19, v132
	v_lshlrev_b32_e32 v27, 16, v133
	v_and_b32_e32 v29, s19, v133
	v_lshlrev_b32_e32 v31, 16, v134
	v_and_b32_e32 v33, s19, v134
	v_lshlrev_b32_e32 v35, 16, v135
	v_and_b32_e32 v37, s19, v135
	v_lshlrev_b32_e32 v42, 16, v139
	v_and_b32_e32 v43, s19, v139
	v_pk_mul_f32 v[38:39], v[6:7], v[22:23] op_sel_hi:[1,0]
	v_pk_mul_f32 v[40:41], v[6:7], v[22:23] op_sel:[0,1] op_sel_hi:[1,1]
	v_pk_fma_f32 v[38:39], v[8:9], v[24:25], v[38:39] op_sel_hi:[1,0,1]
	v_pk_fma_f32 v[40:41], v[8:9], v[24:25], v[40:41] op_sel:[0,1,0] op_sel_hi:[1,1,1]
	v_pk_fma_f32 v[38:39], v[10:11], v[26:27], v[38:39] op_sel_hi:[1,0,1]
	v_pk_fma_f32 v[40:41], v[10:11], v[26:27], v[40:41] op_sel:[0,1,0] op_sel_hi:[1,1,1]
	v_pk_fma_f32 v[38:39], v[12:13], v[28:29], v[38:39] op_sel_hi:[1,0,1]
	v_pk_fma_f32 v[40:41], v[12:13], v[28:29], v[40:41] op_sel:[0,1,0] op_sel_hi:[1,1,1]
	v_pk_fma_f32 v[38:39], v[14:15], v[30:31], v[38:39] op_sel_hi:[1,0,1]
	v_pk_fma_f32 v[40:41], v[14:15], v[30:31], v[40:41] op_sel:[0,1,0] op_sel_hi:[1,1,1]
	v_pk_fma_f32 v[38:39], v[16:17], v[32:33], v[38:39] op_sel_hi:[1,0,1]
	v_pk_fma_f32 v[40:41], v[16:17], v[32:33], v[40:41] op_sel:[0,1,0] op_sel_hi:[1,1,1]
	v_pk_fma_f32 v[38:39], v[18:19], v[34:35], v[38:39] op_sel_hi:[1,0,1]
	v_pk_fma_f32 v[40:41], v[18:19], v[34:35], v[40:41] op_sel:[0,1,0] op_sel_hi:[1,1,1]
	v_pk_fma_f32 v[38:39], v[20:21], v[36:37], v[38:39] op_sel_hi:[1,0,1]
	v_pk_fma_f32 v[40:41], v[20:21], v[36:37], v[40:41] op_sel:[0,1,0] op_sel_hi:[1,1,1]
	v_mul_f32_e32 v50, v136, v51
	v_add_f32_dpp v38, v38, v38 quad_perm:[1,0,3,2] row_mask:0xf bank_mask:0xf bound_ctrl:1
	v_add_f32_dpp v39, v39, v39 quad_perm:[1,0,3,2] row_mask:0xf bank_mask:0xf bound_ctrl:1
	v_add_f32_dpp v40, v40, v40 quad_perm:[1,0,3,2] row_mask:0xf bank_mask:0xf bound_ctrl:1
	v_add_f32_dpp v41, v41, v41 quad_perm:[1,0,3,2] row_mask:0xf bank_mask:0xf bound_ctrl:1
	v_add_f32_dpp v38, v38, v38 quad_perm:[2,3,0,1] row_mask:0xf bank_mask:0xf bound_ctrl:1
	v_add_f32_dpp v39, v39, v39 quad_perm:[2,3,0,1] row_mask:0xf bank_mask:0xf bound_ctrl:1
	v_add_f32_dpp v40, v40, v40 quad_perm:[2,3,0,1] row_mask:0xf bank_mask:0xf bound_ctrl:1
	v_add_f32_dpp v41, v41, v41 quad_perm:[2,3,0,1] row_mask:0xf bank_mask:0xf bound_ctrl:1
	v_add_f32_dpp v38, v38, v38 row_half_mirror row_mask:0xf bank_mask:0xf bound_ctrl:1
	v_add_f32_dpp v39, v39, v39 row_half_mirror row_mask:0xf bank_mask:0xf bound_ctrl:1
	v_add_f32_dpp v40, v40, v40 row_half_mirror row_mask:0xf bank_mask:0xf bound_ctrl:1
	v_add_f32_dpp v41, v41, v41 row_half_mirror row_mask:0xf bank_mask:0xf bound_ctrl:1
	v_add_f32_dpp v38, v38, v38 row_mirror row_mask:0xf bank_mask:0xf bound_ctrl:1
	v_add_f32_dpp v39, v39, v39 row_mirror row_mask:0xf bank_mask:0xf bound_ctrl:1
	v_add_f32_dpp v40, v40, v40 row_mirror row_mask:0xf bank_mask:0xf bound_ctrl:1
	v_add_f32_dpp v41, v41, v41 row_mirror row_mask:0xf bank_mask:0xf bound_ctrl:1
	v_cmp_gt_f32_e32 vcc, 0x2b8cbccc, v50
	v_pk_fma_f32 v[44:45], v[38:39], v[50:51], v[42:43] op_sel:[0,0,0] op_sel_hi:[1,0,1] neg_lo:[1,0,0] neg_hi:[1,0,0]
	v_pk_mul_f32 v[44:45], v[44:45], v[136:137] op_sel:[0,1] op_sel_hi:[1,1]
	v_pk_mul_f32 v[48:49], v[44:45], v[138:139] op_sel_hi:[1,0]
	v_pk_fma_f32 v[48:49], v[40:41], v[50:51], v[48:49] op_sel:[0,0,0] op_sel_hi:[1,0,1]
	s_cbranch_vccnz .Lgdn_rare6
.Lgdn_back6:
	v_rcp_f32_e32 v52, v50
	v_cvt_pk_bf16_f32 v54, v48, v49
	v_pk_mul_f32 v[46:47], v[44:45], v[52:53] op_sel_hi:[1,0]
	v_pk_fma_f32 v[6:7], v[22:23], v[46:47], v[6:7] op_sel_hi:[0,1,1]
	v_pk_fma_f32 v[8:9], v[24:25], v[46:47], v[8:9] op_sel_hi:[0,1,1]
	v_pk_fma_f32 v[10:11], v[26:27], v[46:47], v[10:11] op_sel_hi:[0,1,1]
	v_pk_fma_f32 v[12:13], v[28:29], v[46:47], v[12:13] op_sel_hi:[0,1,1]
	v_pk_fma_f32 v[14:15], v[30:31], v[46:47], v[14:15] op_sel_hi:[0,1,1]
	v_pk_fma_f32 v[16:17], v[32:33], v[46:47], v[16:17] op_sel_hi:[0,1,1]
	v_pk_fma_f32 v[18:19], v[34:35], v[46:47], v[18:19] op_sel_hi:[0,1,1]
	v_pk_fma_f32 v[20:21], v[36:37], v[46:47], v[20:21] op_sel_hi:[0,1,1]
	global_store_dword v3, v54, s[16:17]
	s_add_u32 s16, s16, 0x1000
	s_addc_u32 s17, s17, 0
	global_load_dwordx4 v[128:131], v2, s[12:13]
	global_load_dwordx4 v[132:135], v2, s[12:13] offset:-2048
	global_load_dword v139, v3, s[12:13] offset:2048
	global_load_dwordx3 v[136:138], v1, s[14:15] offset:768
	s_add_u32 s12, s12, 0x1800
	s_addc_u32 s13, s13, 0
	s_waitcnt vmcnt(35)
	v_lshlrev_b32_e32 v22, 16, v140
	v_and_b32_e32 v24, s19, v140
	v_lshlrev_b32_e32 v26, 16, v141
	v_and_b32_e32 v28, s19, v141
	v_lshlrev_b32_e32 v30, 16, v142
	v_and_b32_e32 v32, s19, v142
	v_lshlrev_b32_e32 v34, 16, v143
	v_and_b32_e32 v36, s19, v143
	v_lshlrev_b32_e32 v23, 16, v144
	v_and_b32_e32 v25, s19, v144
	v_lshlrev_b32_e32 v27, 16, v145
	v_and_b32_e32 v29, s19, v145
	v_lshlrev_b32_e32 v31, 16, v146
	v_and_b32_e32 v33, s19, v146
	v_lshlrev_b32_e32 v35, 16, v147
	v_and_b32_e32 v37, s19, v147
	v_lshlrev_b32_e32 v42, 16, v152
	v_and_b32_e32 v43, s19, v152
	v_pk_mul_f32 v[38:39], v[6:7], v[22:23] op_sel_hi:[1,0]
	v_pk_mul_f32 v[40:41], v[6:7], v[22:23] op_sel:[0,1] op_sel_hi:[1,1]
	v_pk_fma_f32 v[38:39], v[8:9], v[24:25], v[38:39] op_sel_hi:[1,0,1]
	v_pk_fma_f32 v[40:41], v[8:9], v[24:25], v[40:41] op_sel:[0,1,0] op_sel_hi:[1,1,1]
	v_pk_fma_f32 v[38:39], v[10:11], v[26:27], v[38:39] op_sel_hi:[1,0,1]
	v_pk_fma_f32 v[40:41], v[10:11], v[26:27], v[40:41] op_sel:[0,1,0] op_sel_hi:[1,1,1]
	v_pk_fma_f32 v[38:39], v[12:13], v[28:29], v[38:39] op_sel_hi:[1,0,1]
	v_pk_fma_f32 v[40:41], v[12:13], v[28:29], v[40:41] op_sel:[0,1,0] op_sel_hi:[1,1,1]
	v_pk_fma_f32 v[38:39], v[14:15], v[30:31], v[38:39] op_sel_hi:[1,0,1]
	v_pk_fma_f32 v[40:41], v[14:15], v[30:31], v[40:41] op_sel:[0,1,0] op_sel_hi:[1,1,1]
	v_pk_fma_f32 v[38:39], v[16:17], v[32:33], v[38:39] op_sel_hi:[1,0,1]
	v_pk_fma_f32 v[40:41], v[16:17], v[32:33], v[40:41] op_sel:[0,1,0] op_sel_hi:[1,1,1]
	v_pk_fma_f32 v[38:39], v[18:19], v[34:35], v[38:39] op_sel_hi:[1,0,1]
	v_pk_fma_f32 v[40:41], v[18:19], v[34:35], v[40:41] op_sel:[0,1,0] op_sel_hi:[1,1,1]
	v_pk_fma_f32 v[38:39], v[20:21], v[36:37], v[38:39] op_sel_hi:[1,0,1]
	v_pk_fma_f32 v[40:41], v[20:21], v[36:37], v[40:41] op_sel:[0,1,0] op_sel_hi:[1,1,1]
	v_mul_f32_e32 v51, v148, v50
	v_add_f32_dpp v38, v38, v38 quad_perm:[1,0,3,2] row_mask:0xf bank_mask:0xf bound_ctrl:1
	v_add_f32_dpp v39, v39, v39 quad_perm:[1,0,3,2] row_mask:0xf bank_mask:0xf bound_ctrl:1
	v_add_f32_dpp v40, v40, v40 quad_perm:[1,0,3,2] row_mask:0xf bank_mask:0xf bound_ctrl:1
	v_add_f32_dpp v41, v41, v41 quad_perm:[1,0,3,2] row_mask:0xf bank_mask:0xf bound_ctrl:1
	v_add_f32_dpp v38, v38, v38 quad_perm:[2,3,0,1] row_mask:0xf bank_mask:0xf bound_ctrl:1
	v_add_f32_dpp v39, v39, v39 quad_perm:[2,3,0,1] row_mask:0xf bank_mask:0xf bound_ctrl:1
	v_add_f32_dpp v40, v40, v40 quad_perm:[2,3,0,1] row_mask:0xf bank_mask:0xf bound_ctrl:1
	v_add_f32_dpp v41, v41, v41 quad_perm:[2,3,0,1] row_mask:0xf bank_mask:0xf bound_ctrl:1
	v_add_f32_dpp v38, v38, v38 row_half_mirror row_mask:0xf bank_mask:0xf bound_ctrl:1
	v_add_f32_dpp v39, v39, v39 row_half_mirror row_mask:0xf bank_mask:0xf bound_ctrl:1
	v_add_f32_dpp v40, v40, v40 row_half_mirror row_mask:0xf bank_mask:0xf bound_ctrl:1
	v_add_f32_dpp v41, v41, v41 row_half_mirror row_mask:0xf bank_mask:0xf bound_ctrl:1
	v_add_f32_dpp v38, v38, v38 row_mirror row_mask:0xf bank_mask:0xf bound_ctrl:1
	v_add_f32_dpp v39, v39, v39 row_mirror row_mask:0xf bank_mask:0xf bound_ctrl:1
	v_add_f32_dpp v40, v40, v40 row_mirror row_mask:0xf bank_mask:0xf bound_ctrl:1
	v_add_f32_dpp v41, v41, v41 row_mirror row_mask:0xf bank_mask:0xf bound_ctrl:1
	v_cmp_gt_f32_e32 vcc, 0x2b8cbccc, v51
	v_pk_fma_f32 v[44:45], v[38:39], v[50:51], v[42:43] op_sel:[0,1,0] op_sel_hi:[1,1,1] neg_lo:[1,0,0] neg_hi:[1,0,0]
	v_pk_mul_f32 v[44:45], v[44:45], v[148:149] op_sel:[0,1] op_sel_hi:[1,1]
	v_pk_mul_f32 v[48:49], v[44:45], v[150:151] op_sel_hi:[1,0]
	v_pk_fma_f32 v[48:49], v[40:41], v[50:51], v[48:49] op_sel:[0,1,0] op_sel_hi:[1,1,1]
	s_cbranch_vccnz .Lgdn_rare7
.Lgdn_back7:
	v_rcp_f32_e32 v52, v51
	v_cvt_pk_bf16_f32 v54, v48, v49
	v_pk_mul_f32 v[46:47], v[44:45], v[52:53] op_sel_hi:[1,0]
	v_pk_fma_f32 v[6:7], v[22:23], v[46:47], v[6:7] op_sel_hi:[0,1,1]
	v_pk_fma_f32 v[8:9], v[24:25], v[46:47], v[8:9] op_sel_hi:[0,1,1]
	v_pk_fma_f32 v[10:11], v[26:27], v[46:47], v[10:11] op_sel_hi:[0,1,1]
	v_pk_fma_f32 v[12:13], v[28:29], v[46:47], v[12:13] op_sel_hi:[0,1,1]
	v_pk_fma_f32 v[14:15], v[30:31], v[46:47], v[14:15] op_sel_hi:[0,1,1]
	v_pk_fma_f32 v[16:17], v[32:33], v[46:47], v[16:17] op_sel_hi:[0,1,1]
	v_pk_fma_f32 v[18:19], v[34:35], v[46:47], v[18:19] op_sel_hi:[0,1,1]
	v_pk_fma_f32 v[20:21], v[36:37], v[46:47], v[20:21] op_sel_hi:[0,1,1]
	global_store_dword v3, v54, s[16:17]
	s_add_u32 s16, s16, 0x1000
	s_addc_u32 s17, s17, 0
	global_load_dwordx4 v[140:143], v2, s[12:13]
	global_load_dwordx4 v[144:147], v2, s[12:13] offset:-2048
	global_load_dword v152, v3, s[12:13] offset:2048
	global_load_dwordx3 v[148:150], v1, s[14:15] offset:896
	s_add_u32 s12, s12, 0x1800
	s_addc_u32 s13, s13, 0
	s_add_u32 s14, s14, 0x400
	s_addc_u32 s15, s15, 0
	s_add_i32 s18, s18, 8
	s_cmpk_lt_u32 s18, 0x800
	s_cbranch_scc1 .Lgdn_loop
	v_pk_mul_f32 v[154:155], v[6:7], v[50:51] op_sel:[0,1] op_sel_hi:[1,1]
	global_store_dwordx2 v153, v[154:155], s[20:21] offset:0
	v_pk_mul_f32 v[156:157], v[8:9], v[50:51] op_sel:[0,1] op_sel_hi:[1,1]
	global_store_dwordx2 v153, v[156:157], s[20:21] offset:512
	v_pk_mul_f32 v[154:155], v[10:11], v[50:51] op_sel:[0,1] op_sel_hi:[1,1]
	global_store_dwordx2 v153, v[154:155], s[20:21] offset:1024
	v_pk_mul_f32 v[156:157], v[12:13], v[50:51] op_sel:[0,1] op_sel_hi:[1,1]
	global_store_dwordx2 v153, v[156:157], s[20:21] offset:1536
	v_pk_mul_f32 v[154:155], v[14:15], v[50:51] op_sel:[0,1] op_sel_hi:[1,1]
	global_store_dwordx2 v153, v[154:155], s[20:21] offset:2048
	v_pk_mul_f32 v[156:157], v[16:17], v[50:51] op_sel:[0,1] op_sel_hi:[1,1]
	global_store_dwordx2 v153, v[156:157], s[20:21] offset:2560
	v_pk_mul_f32 v[154:155], v[18:19], v[50:51] op_sel:[0,1] op_sel_hi:[1,1]
	global_store_dwordx2 v153, v[154:155], s[20:21] offset:3072
	v_pk_mul_f32 v[156:157], v[20:21], v[50:51] op_sel:[0,1] op_sel_hi:[1,1]
	global_store_dwordx2 v153, v[156:157], s[20:21] offset:3584
	s_add_i32 s27, s27, s28
	s_waitcnt vmcnt(0)
	s_cmpk_lt_i32 s27, 0x400
	s_cbranch_scc1 .Lgdn_item
	s_branch .LBB0_232
.Lgdn_rare0:
	v_pk_mul_f32 v[6:7], v[6:7], v[50:51] op_sel:[0,0] op_sel_hi:[1,0]
	v_pk_mul_f32 v[8:9], v[8:9], v[50:51] op_sel:[0,0] op_sel_hi:[1,0]
	v_pk_mul_f32 v[10:11], v[10:11], v[50:51] op_sel:[0,0] op_sel_hi:[1,0]
	v_pk_mul_f32 v[12:13], v[12:13], v[50:51] op_sel:[0,0] op_sel_hi:[1,0]
	v_pk_mul_f32 v[14:15], v[14:15], v[50:51] op_sel:[0,0] op_sel_hi:[1,0]
	v_pk_mul_f32 v[16:17], v[16:17], v[50:51] op_sel:[0,0] op_sel_hi:[1,0]
	v_pk_mul_f32 v[18:19], v[18:19], v[50:51] op_sel:[0,0] op_sel_hi:[1,0]
	v_pk_mul_f32 v[20:21], v[20:21], v[50:51] op_sel:[0,0] op_sel_hi:[1,0]
	v_mov_b32_e32 v50, 1.0
	s_branch .Lgdn_back0
.Lgdn_rare1:
	v_pk_mul_f32 v[6:7], v[6:7], v[50:51] op_sel:[0,1] op_sel_hi:[1,1]
	v_pk_mul_f32 v[8:9], v[8:9], v[50:51] op_sel:[0,1] op_sel_hi:[1,1]
	v_pk_mul_f32 v[10:11], v[10:11], v[50:51] op_sel:[0,1] op_sel_hi:[1,1]
	v_pk_mul_f32 v[12:13], v[12:13], v[50:51] op_sel:[0,1] op_sel_hi:[1,1]
	v_pk_mul_f32 v[14:15], v[14:15], v[50:51] op_sel:[0,1] op_sel_hi:[1,1]
	v_pk_mul_f32 v[16:17], v[16:17], v[50:51] op_sel:[0,1] op_sel_hi:[1,1]
	v_pk_mul_f32 v[18:19], v[18:19], v[50:51] op_sel:[0,1] op_sel_hi:[1,1]
	v_pk_mul_f32 v[20:21], v[20:21], v[50:51] op_sel:[0,1] op_sel_hi:[1,1]
	v_mov_b32_e32 v51, 1.0
	s_branch .Lgdn_back1
